# LRU conv stage: second half's 8 parameter reads issued behind the first half's (fresh registers, counted waits re-based)
# baseline (speedup 1.0000x reference)
; DEVI unsigned pk2(float lo, float hi) { f32x2 v = {lo, hi}; bf16x2_t b = __builtin_convertvector(v, bf16x2_t); return __builtin_bit_cast(unsigned, b); }
; DEVI float bflo(unsigned u) { return __uint_as_float(u << 16); }
; DEVI float bfhi(unsigned u) { return __uint_as_float(u & 0xffff0000u); }
; template <bool PASS_C>
; DEVI void lru_item(const P& p, int item, int next_item, uint4& u0, uint4& u1, uint4& u2, float& cpre, char* smem) {
;     ...
;     {
;         const int tok = tid >> 2, cg0 = (tid & 3) * 16;
;         uint4 r[4][2];
; #pragma unroll
;         for (int k = 0; k < 4; ++k) { r[k][0] = *(const uint4*)(us + (tok + k) * 64 + cg0); r[k][1] = *(const uint4*)(us + (tok + k) * 64 + cg0 + 8); }
;         float val[16];
; #pragma unroll
;         for (int e = 0; e < 16; ++e) {
;             const int ch = cg0 + e;
;             float a = prm[4 * 64 + ch];
; #pragma unroll
;             for (int k = 0; k < 4; ++k) {
;                 const uint4 q = r[k][e >> 3];
;                 const unsigned wd = ((e >> 1) & 3) == 0 ? q.x : (((e >> 1) & 3) == 1 ? q.y : (((e >> 1) & 3) == 2 ? q.z : q.w));
;                 a += prm[k * 64 + ch] * ((e & 1) ? bfhi(wd) : bflo(wd));
;             }
;             val[e] = a;
;         }
;         uint4 o;
;         o.x = pk2(val[0], val[1]); o.y = pk2(val[2], val[3]); o.z = pk2(val[4], val[5]); o.w = pk2(val[6], val[7]);
;         *(uint4*)(ucb + tok * 128 + ((((cg0 >> 3) + 0) ^ (tok & 7)) << 4)) = o;
;         o.x = pk2(val[8], val[9]); o.y = pk2(val[10], val[11]); o.z = pk2(val[12], val[13]); o.w = pk2(val[14], val[15]);
;         *(uint4*)(ucb + tok * 128 + ((((cg0 >> 3) + 1) ^ (tok & 7)) << 4)) = o;
;     }
.LBB0_510:
	s_waitcnt lgkmcnt(0)
	s_barrier
	ds_read_b128 v[32:35], v118 offset:35840
	ds_read_b128 v[12:15], v118 offset:35856
	ds_read_b128 v[36:39], v118 offset:35968
	ds_read_b128 v[16:19], v118 offset:35984
	ds_read_b128 v[40:43], v118 offset:36096
	ds_read_b128 v[20:23], v118 offset:36112
	ds_read_b128 v[44:47], v118 offset:36224
	ds_read_b128 v[24:27], v118 offset:36240
	ds_read_b128 v[48:51], v111 offset:33792
	ds_read_b128 v[52:55], v111 offset:32768
	ds_read_b128 v[56:59], v111 offset:32784
	ds_read_b128 v[60:63], v111 offset:32800
	ds_read_b128 v[28:31], v111 offset:32816
	ds_read_b128 v[64:67], v111 offset:33024
	ds_read_b128 v[92:95], v111 offset:33808
	s_waitcnt lgkmcnt(14)
	v_lshlrev_b32_e32 v96, 16, v32
	v_and_b32_e32 v97, 0xffff0000, v32
	s_waitcnt lgkmcnt(5)
	v_pk_fma_f32 v[48:49], v[52:53], v[96:97], v[48:49]
	ds_read_b128 v[96:99], v111 offset:33280
	ds_read_b128 v[146:149], v111 offset:33536
	ds_read_b128 v[150:153], v111 offset:33040
	v_lshlrev_b32_e32 v32, 16, v33
	v_and_b32_e32 v33, 0xffff0000, v33
	v_lshlrev_b32_e32 v154, 16, v36
	v_and_b32_e32 v155, 0xffff0000, v36
	v_lshlrev_b32_e32 v36, 16, v37
	v_and_b32_e32 v37, 0xffff0000, v37
	v_pk_fma_f32 v[32:33], v[54:55], v[32:33], v[50:51]
	v_lshlrev_b32_e32 v158, 16, v40
	v_and_b32_e32 v159, 0xffff0000, v40
	s_waitcnt lgkmcnt(4)
	v_pk_fma_f32 v[48:49], v[64:65], v[154:155], v[48:49]
	ds_read_b128 v[154:157], v111 offset:33296
	v_lshlrev_b32_e32 v40, 16, v41
	v_and_b32_e32 v41, 0xffff0000, v41
	v_pk_fma_f32 v[32:33], v[66:67], v[36:37], v[32:33]
	v_lshlrev_b32_e32 v162, 16, v44
	v_and_b32_e32 v163, 0xffff0000, v44
	s_waitcnt lgkmcnt(3)
	v_pk_fma_f32 v[48:49], v[96:97], v[158:159], v[48:49]
	ds_read_b128 v[158:161], v111 offset:33552
	ds_read_b128 v[232:235], v111 offset:33824
	ds_read_b128 v[236:239], v111 offset:33056
	ds_read_b128 v[240:243], v111 offset:33840
	ds_read_b128 v[244:247], v111 offset:33312
	ds_read_b128 v[248:251], v111 offset:33568
	ds_read_b128 v[252:255], v111 offset:33072
	ds_read_b128 v[218:221], v111 offset:33328
	ds_read_b128 v[222:225], v111 offset:33584
	v_lshlrev_b32_e32 v44, 16, v45
	v_and_b32_e32 v45, 0xffff0000, v45
	v_pk_fma_f32 v[32:33], v[98:99], v[40:41], v[32:33]
	v_lshlrev_b32_e32 v36, 16, v38
	s_waitcnt lgkmcnt(11)
	v_pk_fma_f32 v[98:99], v[148:149], v[44:45], v[32:33]
	v_lshlrev_b32_e32 v32, 16, v34
	v_and_b32_e32 v33, 0xffff0000, v34
	v_and_b32_e32 v37, 0xffff0000, v38
	v_pk_fma_f32 v[32:33], v[56:57], v[32:33], v[92:93]
	v_lshlrev_b32_e32 v40, 16, v42
	v_and_b32_e32 v41, 0xffff0000, v42
	s_waitcnt lgkmcnt(10)
	v_pk_fma_f32 v[32:33], v[150:151], v[36:37], v[32:33]
	v_lshlrev_b32_e32 v44, 16, v46
	v_and_b32_e32 v45, 0xffff0000, v46
	s_waitcnt lgkmcnt(9)
	v_pk_fma_f32 v[32:33], v[154:155], v[40:41], v[32:33]
	v_lshlrev_b32_e32 v34, 16, v39
	s_waitcnt lgkmcnt(8)
	v_pk_fma_f32 v[92:93], v[158:159], v[44:45], v[32:33]
	v_lshlrev_b32_e32 v32, 16, v35
	v_and_b32_e32 v33, 0xffff0000, v35
	v_and_b32_e32 v35, 0xffff0000, v39
	v_pk_fma_f32 v[32:33], v[58:59], v[32:33], v[94:95]
	v_lshlrev_b32_e32 v36, 16, v43
	v_and_b32_e32 v37, 0xffff0000, v43
	v_pk_fma_f32 v[32:33], v[152:153], v[34:35], v[32:33]
	v_lshlrev_b32_e32 v38, 16, v47
	v_and_b32_e32 v39, 0xffff0000, v47
	v_pk_fma_f32 v[32:33], v[156:157], v[36:37], v[32:33]
	v_lshlrev_b32_e32 v44, 16, v12
	v_pk_fma_f32 v[94:95], v[160:161], v[38:39], v[32:33]
	v_and_b32_e32 v45, 0xffff0000, v12
	v_pk_fma_f32 v[96:97], v[146:147], v[162:163], v[48:49]
	v_lshlrev_b32_e32 v12, 16, v13
	s_waitcnt lgkmcnt(7)
	v_pk_fma_f32 v[32:33], v[60:61], v[44:45], v[232:233]
	v_and_b32_e32 v13, 0xffff0000, v13
	v_lshlrev_b32_e32 v56, 16, v16
	v_and_b32_e32 v57, 0xffff0000, v16
	v_lshlrev_b32_e32 v16, 16, v17
	v_and_b32_e32 v17, 0xffff0000, v17
	v_pk_fma_f32 v[12:13], v[62:63], v[12:13], v[234:235]
	v_lshlrev_b32_e32 v64, 16, v20
	v_and_b32_e32 v65, 0xffff0000, v20
	s_waitcnt lgkmcnt(6)
	v_pk_fma_f32 v[32:33], v[236:237], v[56:57], v[32:33]
	v_lshlrev_b32_e32 v20, 16, v21
	v_and_b32_e32 v21, 0xffff0000, v21
	v_pk_fma_f32 v[12:13], v[238:239], v[16:17], v[12:13]
	v_lshlrev_b32_e32 v146, 16, v24
	v_and_b32_e32 v147, 0xffff0000, v24
	s_waitcnt lgkmcnt(4)
	v_pk_fma_f32 v[32:33], v[244:245], v[64:65], v[32:33]
	v_lshlrev_b32_e32 v24, 16, v25
	v_and_b32_e32 v25, 0xffff0000, v25
	v_pk_fma_f32 v[12:13], v[246:247], v[20:21], v[12:13]
	v_lshlrev_b32_e32 v20, 16, v18
	s_waitcnt lgkmcnt(3)
	v_pk_fma_f32 v[16:17], v[250:251], v[24:25], v[12:13]
	v_lshlrev_b32_e32 v12, 16, v14
	v_and_b32_e32 v13, 0xffff0000, v14
	v_and_b32_e32 v21, 0xffff0000, v18
	v_pk_fma_f32 v[12:13], v[28:29], v[12:13], v[240:241]
	v_lshlrev_b32_e32 v24, 16, v22
	v_and_b32_e32 v25, 0xffff0000, v22
	s_waitcnt lgkmcnt(2)
	v_pk_fma_f32 v[12:13], v[252:253], v[20:21], v[12:13]
	v_lshlrev_b32_e32 v34, 16, v26
	v_and_b32_e32 v35, 0xffff0000, v26
	s_waitcnt lgkmcnt(1)
	v_pk_fma_f32 v[12:13], v[218:219], v[24:25], v[12:13]
	v_lshlrev_b32_e32 v14, 16, v19
	s_waitcnt lgkmcnt(0)
	v_pk_fma_f32 v[20:21], v[222:223], v[34:35], v[12:13]
	v_lshlrev_b32_e32 v12, 16, v15
	v_and_b32_e32 v13, 0xffff0000, v15
	v_and_b32_e32 v15, 0xffff0000, v19
	v_pk_fma_f32 v[12:13], v[30:31], v[12:13], v[242:243]
	v_lshlrev_b32_e32 v18, 16, v23
	v_and_b32_e32 v19, 0xffff0000, v23
	v_pk_fma_f32 v[12:13], v[254:255], v[14:15], v[12:13]
	v_lshlrev_b32_e32 v22, 16, v27
	v_and_b32_e32 v23, 0xffff0000, v27
	v_pk_fma_f32 v[12:13], v[220:221], v[18:19], v[12:13]
	v_pk_fma_f32 v[32:33], v[248:249], v[146:147], v[32:33]
	v_pk_fma_f32 v[18:19], v[224:225], v[22:23], v[12:13]
	v_cvt_pk_bf16_f32 v12, v96, v97
	v_cvt_pk_bf16_f32 v13, v98, v99
	v_cvt_pk_bf16_f32 v14, v92, v93
	v_cvt_pk_bf16_f32 v15, v94, v95
	ds_write_b128 v119, v[12:15] offset:44544
	v_cvt_pk_bf16_f32 v12, v32, v33
	v_cvt_pk_bf16_f32 v13, v16, v17
	v_cvt_pk_bf16_f32 v14, v20, v21
	v_cvt_pk_bf16_f32 v15, v18, v19
	ds_write_b128 v120, v[12:15] offset:44544
	v_add_u32_e32 v12, v113, v114
	s_waitcnt lgkmcnt(0)
	s_barrier
; template <bool PASS_C>
; DEVI void lru_item(const P& p, int item, int next_item, uint4& u0, uint4& u1, uint4& u2, float& cpre, char* smem) {
;     ...
;     f32x4 acc[16];
; #pragma unroll
;     for (int n = 0; n < 16; ++n) acc[n] = (f32x4){0.f, 0.f, 0.f, 0.f};
;     {
;         bf16x8 af[2];
; #pragma unroll
;         for (int kk = 0; kk < 2; ++kk) af[kk] = *(const bf16x8*)(ucb + (16 * w + fr) * 128 + (((kk * 4 + fq) ^ (fr & 7)) << 4));
; #pragma unroll
;         for (int n = 0; n < 16; ++n)
; #pragma unroll
;             for (int kk = 0; kk < 2; ++kk) {
;                 const bf16x8 bfr = *(const bf16x8*)(smem + (16 * n + fr) * 128 + (((kk * 4 + fq) ^ (fr & 7)) << 4));
;                 acc[n] = __builtin_amdgcn_mfma_f32_16x16x32_bf16(af[kk], bfr, acc[n], 0, 0, 0);
;             }
;     }
	v_add_u32_e32 v75, v112, v114
	v_add_u32_e32 v20, v113, v115
	v_add_u32_e32 v77, v112, v115
	ds_read_b128 v[12:15], v12 offset:44544
	ds_read_b128 v[92:95], v20 offset:44544
	ds_read_b32 v83, v116 offset:35072
	ds_read_b128 v[232:235], v75
	ds_read_b128 v[236:239], v77
	ds_read_b128 v[240:243], v75 offset:2048
	ds_read_b128 v[244:247], v77 offset:2048
	ds_read_b128 v[248:251], v75 offset:4096
	ds_read_b128 v[158:161], v77 offset:4096
	ds_read_b128 v[252:255], v75 offset:6144
	ds_read_b128 v[218:221], v77 offset:6144
	s_waitcnt lgkmcnt(4)
	v_mfma_f32_16x16x32_bf16 v[146:149], v[12:15], v[232:235], 0
	ds_read_b128 v[222:225], v75 offset:8192
	ds_read_b128 v[226:229], v77 offset:8192
	ds_read_b128 v[96:99], v75 offset:10240
	ds_read_b128 v[154:157], v77 offset:10240
	v_mfma_f32_16x16x32_bf16 v[56:59], v[12:15], v[240:243], 0
	v_mfma_f32_16x16x32_bf16 v[146:149], v[92:95], v[236:239], v[146:149]
	v_mfma_f32_16x16x32_bf16 v[56:59], v[92:95], v[244:247], v[56:59]
	s_waitcnt lgkmcnt(4)
	v_mfma_f32_16x16x32_bf16 v[40:43], v[12:15], v[248:251], 0
	ds_read_b128 v[232:235], v75 offset:12288
	ds_read_b128 v[236:239], v77 offset:12288
	ds_read_b128 v[240:243], v75 offset:14336
	ds_read_b128 v[244:247], v77 offset:14336
	v_mfma_f32_16x16x32_bf16 v[24:27], v[12:15], v[252:255], 0
	v_mfma_f32_16x16x32_bf16 v[40:43], v[92:95], v[158:161], v[40:43]
	v_mfma_f32_16x16x32_bf16 v[24:27], v[92:95], v[218:221], v[24:27]
	s_waitcnt lgkmcnt(4)
	v_mfma_f32_16x16x32_bf16 v[150:153], v[12:15], v[222:225], 0
	ds_read_b128 v[248:251], v75 offset:16384
	ds_read_b128 v[158:161], v77 offset:16384
	ds_read_b128 v[252:255], v75 offset:18432
	ds_read_b128 v[218:221], v77 offset:18432
	v_mfma_f32_16x16x32_bf16 v[52:55], v[12:15], v[96:99], 0
	v_mfma_f32_16x16x32_bf16 v[150:153], v[92:95], v[226:229], v[150:153]
	v_mfma_f32_16x16x32_bf16 v[52:55], v[92:95], v[154:157], v[52:55]
	s_waitcnt lgkmcnt(4)
	v_mfma_f32_16x16x32_bf16 v[36:39], v[12:15], v[232:235], 0
	ds_read_b128 v[222:225], v75 offset:20480
	ds_read_b128 v[226:229], v77 offset:20480
	ds_read_b128 v[96:99], v75 offset:22528
	ds_read_b128 v[154:157], v77 offset:22528
	v_mfma_f32_16x16x32_bf16 v[20:23], v[12:15], v[240:243], 0
	v_mfma_f32_16x16x32_bf16 v[36:39], v[92:95], v[236:239], v[36:39]
	v_mfma_f32_16x16x32_bf16 v[20:23], v[92:95], v[244:247], v[20:23]
	s_waitcnt lgkmcnt(4)
	v_mfma_f32_16x16x32_bf16 v[64:67], v[12:15], v[248:251], 0
	ds_read_b128 v[232:235], v75 offset:24576
	ds_read_b128 v[236:239], v77 offset:24576
	ds_read_b128 v[240:243], v75 offset:26624
	ds_read_b128 v[244:247], v77 offset:26624
	v_mfma_f32_16x16x32_bf16 v[48:51], v[12:15], v[252:255], 0
	v_mfma_f32_16x16x32_bf16 v[64:67], v[92:95], v[158:161], v[64:67]
	v_mfma_f32_16x16x32_bf16 v[48:51], v[92:95], v[218:221], v[48:51]
	s_waitcnt lgkmcnt(4)
	v_mfma_f32_16x16x32_bf16 v[32:35], v[12:15], v[222:225], 0
	ds_read_b128 v[248:251], v75 offset:28672
	ds_read_b128 v[252:255], v75 offset:30720
	ds_read_b128 v[158:161], v77 offset:28672
	v_mfma_f32_16x16x32_bf16 v[16:19], v[12:15], v[96:99], 0
	v_mfma_f32_16x16x32_bf16 v[32:35], v[92:95], v[226:229], v[32:35]
	v_mfma_f32_16x16x32_bf16 v[16:19], v[92:95], v[154:157], v[16:19]
	s_waitcnt lgkmcnt(3)
	v_mfma_f32_16x16x32_bf16 v[60:63], v[12:15], v[232:235], 0
	v_mfma_f32_16x16x32_bf16 v[44:47], v[12:15], v[240:243], 0
	v_mfma_f32_16x16x32_bf16 v[60:63], v[92:95], v[236:239], v[60:63]
	v_mfma_f32_16x16x32_bf16 v[44:47], v[92:95], v[244:247], v[44:47]
	s_waitcnt lgkmcnt(1)
; template <bool PASS_C>
; DEVI void lru_item(const P& p, int item, int next_item, uint4& u0, uint4& u1, uint4& u2, float& cpre, char* smem) {
;     ...
;                 acc[n] = __builtin_amdgcn_mfma_f32_16x16x32_bf16(af[kk], bfr, acc[n], 0, 0, 0);
;             }
;     }
;     float av[4][2][4], bv[4][2][4], apre[4][2], bpre[4][2];
; #pragma unroll
;     for (int nn = 0; nn < 4; ++nn) {
;         const int ch = 16 * nn + fr;
;         float uc[4];
; #pragma unroll
;         for (int j = 0; j < 4; ++j) {
;             const int tl = 16 * w + 4 * fq + j;
;             uc[j] = bf2f(*(const bf16_t*)(ucb + tl * 128 + ((((ch >> 3)) ^ (tl & 7)) << 4) + (ch & 7) * 2));
;         }
; #pragma unroll
;         for (int d = 0; d < 2; ++d) {
;             const float ba = prm[(5 + d) * 64 + ch], bx = prm[(7 + d) * 64 + ch], nsp8 = prm[(9 + d) * 64 + ch];
; #pragma unroll
;             for (int j = 0; j < 4; ++j) {
;                 const float r = __builtin_amdgcn_rcpf(1.0f + __builtin_amdgcn_exp2f(__builtin_fmaf(acc[(2 * d) * 4 + nn][j], -LOG2E, ba)));
;                 const float ig = __builtin_amdgcn_rcpf(1.0f + __builtin_amdgcn_exp2f(__builtin_fmaf(acc[(2 * d + 1) * 4 + nn][j], -LOG2E, bx)));
;                 const float a_ = __builtin_amdgcn_exp2f(nsp8 * r);
;                 av[nn][d][j] = a_;
;                 bv[nn][d][j] = __builtin_amdgcn_sqrtf(__builtin_fmaf(-a_, a_, 1.0f)) * ig * uc[j];
;             }
;             float A = 1.f, Bq = 0.f;
;             if (d == 0) {
; #pragma unroll
;                 for (int j = 0; j < 4; ++j) { Bq = av[nn][d][j] * Bq + bv[nn][d][j]; A *= av[nn][d][j]; }
;             } else {
; #pragma unroll
;                 for (int j = 3; j >= 0; --j) { Bq = av[nn][d][j] * Bq + bv[nn][d][j]; A *= av[nn][d][j]; }
;             }
;             float Ag[4], Bg[4];
;             rowgather4(A, Ag); rowgather4(Bq, Bg);
;             float AW = 1.f, BW = 0.f, AP = 1.f, BP = 0.f;
;             if (d == 0) {
; #pragma unroll
;                 for (int g = 0; g < 4; ++g) {
;                     if (g == fq) { AP = AW; BP = BW; }
;                     BW = Ag[g] * BW + Bg[g]; AW *= Ag[g];
;                 }
;             } else {
; #pragma unroll
;                 for (int g = 3; g >= 0; --g) {
;                     if (g == fq) { AP = AW; BP = BW; }
;                     BW = Ag[g] * BW + Bg[g]; AW *= Ag[g];
;                 }
;             }
	v_mfma_f32_16x16x32_bf16 v[28:31], v[12:15], v[248:251], 0
	v_mfma_f32_16x16x32_bf16 v[12:15], v[12:15], v[252:255], 0
	ds_read_b128 v[96:99], v77 offset:30720
	ds_read2st64_b32 v[154:155], v116 offset0:133 offset1:135
	ds_read_u16 v246, v121 offset:44544
	ds_read_u16 v247, v122 offset:44544
	ds_read_u16 v248, v123 offset:44544
	ds_read_u16 v249, v124 offset:44544
	ds_read2st64_b32 v[232:233], v116 offset0:134 offset1:136
	ds_read_b32 v250, v116 offset:35328
	v_add_u32_e32 v217, 64, v116
	ds_read2st64_b32 v[234:235], v217 offset0:133 offset1:135
	ds_read_u16 v251, v125 offset:44544
	ds_read_u16 v252, v126 offset:44544
	ds_read_u16 v253, v127 offset:44544
	ds_read_u16 v254, v128 offset:44544
	ds_read_b32 v255, v116 offset:35136
	v_add_u32_e32 v217, 64, v116
	ds_read2st64_b32 v[236:237], v217 offset0:134 offset1:136
	ds_read_b32 v218, v116 offset:35392
	v_add_u32_e32 v217, 0x80, v116
	ds_read2st64_b32 v[238:239], v217 offset0:133 offset1:135
	ds_read_u16 v219, v129 offset:44544
	ds_read_u16 v220, v130 offset:44544
	ds_read_u16 v221, v131 offset:44544
	ds_read_u16 v222, v132 offset:44544
	ds_read_b32 v223, v116 offset:35200
	v_add_u32_e32 v217, 0x80, v116
	ds_read2st64_b32 v[240:241], v217 offset0:134 offset1:136
	ds_read_b32 v224, v116 offset:35456
	v_add_u32_e32 v217, 0xc0, v116
	ds_read2st64_b32 v[242:243], v217 offset0:133 offset1:135
	ds_read_u16 v225, v133 offset:44544
	ds_read_u16 v226, v134 offset:44544
	ds_read_u16 v227, v135 offset:44544
	ds_read_u16 v228, v136 offset:44544
	ds_read_b32 v229, v116 offset:35264
	v_add_u32_e32 v217, 0xc0, v116
	ds_read2st64_b32 v[244:245], v217 offset0:134 offset1:136
	ds_read_b32 v231, v116 offset:35520
	s_waitcnt lgkmcnt(0)
	v_fmamk_f32 v81, v146, 0xbfb8aa3b, v154
	v_exp_f32_e32 v81, v81
	v_fmamk_f32 v91, v149, 0xbfb8aa3b, v154
	v_exp_f32_e32 v91, v91
	v_mfma_f32_16x16x32_bf16 v[28:31], v[92:95], v[158:161], v[28:31]
	v_add_f32_e32 v81, 1.0, v81
	v_rcp_f32_e32 v87, v81
	v_fmamk_f32 v81, v147, 0xbfb8aa3b, v154
	v_exp_f32_e32 v89, v81
	v_lshlrev_b32_e32 v81, 16, v249
	v_mul_f32_e32 v85, v83, v87
	v_mfma_f32_16x16x32_bf16 v[12:15], v[92:95], v[96:99], v[12:15]
	v_add_f32_e32 v87, 1.0, v89
	v_fmamk_f32 v89, v148, 0xbfb8aa3b, v154
	v_exp_f32_e32 v89, v89
	v_add_f32_e32 v91, 1.0, v91
	v_fmamk_f32 v93, v150, 0xbfb8aa3b, v155
	v_rcp_f32_e32 v87, v87
	v_add_f32_e32 v89, 1.0, v89
	v_exp_f32_e32 v85, v85
	v_rcp_f32_e32 v89, v89
	v_rcp_f32_e32 v91, v91
	v_exp_f32_e32 v93, v93
	v_mul_f32_e32 v87, v83, v87
	v_mul_f32_e32 v89, v83, v89
	v_mul_f32_e32 v83, v83, v91
	v_add_f32_e32 v91, 1.0, v93
	v_fma_f32 v93, -v85, v85, 1.0
	v_rcp_f32_e32 v91, v91
	v_sqrt_f32_e32 v93, v93
	v_fmamk_f32 v94, v151, 0xbfb8aa3b, v155
	v_exp_f32_e32 v87, v87
	v_exp_f32_e32 v94, v94
	v_lshlrev_b32_e32 v75, 16, v246
	v_mul_f32_e32 v91, v91, v93
	v_mul_f32_e32 v91, v91, v75
	v_mul_f32_e32 v92, v85, v87
	v_fmac_f32_e32 v91, 0, v85
	v_add_f32_e32 v85, 1.0, v94
	v_fma_f32 v93, -v87, v87, 1.0
	v_rcp_f32_e32 v85, v85
	v_sqrt_f32_e32 v93, v93
	v_mul_f32_e32 v87, v87, v91
	v_fmamk_f32 v91, v152, 0xbfb8aa3b, v155
	v_exp_f32_e32 v89, v89
	v_exp_f32_e32 v91, v91
	v_lshlrev_b32_e32 v77, 16, v247
	v_mul_f32_e32 v85, v85, v93
	v_fmac_f32_e32 v87, v85, v77
	v_fmamk_f32 v155, v153, 0xbfb8aa3b, v155
	v_exp_f32_e32 v83, v83
	v_mul_f32_e32 v85, v89, v87
	v_add_f32_e32 v87, 1.0, v91
	v_exp_f32_e32 v91, v155
	v_mul_f32_e32 v92, v89, v92
	v_fma_f32 v89, -v89, v89, 1.0
	v_rcp_f32_e32 v87, v87
	v_sqrt_f32_e32 v89, v89
	v_add_f32_e32 v91, 1.0, v91
	v_fma_f32 v93, -v83, v83, 1.0
	v_rcp_f32_e32 v91, v91
	v_sqrt_f32_e32 v93, v93
	v_lshlrev_b32_e32 v79, 16, v248
	v_mul_f32_e32 v87, v87, v89
	v_fmac_f32_e32 v85, v87, v79
	v_mul_f32_e32 v92, v83, v92
	v_mul_f32_e32 v83, v83, v85
	v_mul_f32_e32 v85, v91, v93
	v_fmac_f32_e32 v83, v85, v81
	v_mov_b32_e32 v96, v92
	v_mov_b32_e32 v85, v83
	s_nop 0
	v_permlane16_swap_b32_e32 v92, v96
	v_permlane16_swap_b32_e32 v83, v85
	v_mov_b32_e32 v94, v92
	v_mov_b32_e32 v95, v96
	v_mov_b32_e32 v97, v83
	v_mov_b32_e32 v99, v85
	v_permlane32_swap_b32_e32 v92, v94
	v_permlane32_swap_b32_e32 v96, v95
	v_permlane32_swap_b32_e32 v83, v97
	v_permlane32_swap_b32_e32 v85, v99
	s_and_saveexec_b64 s[12:13], s[8:9]
	s_cbranch_execz .LBB0_512
	v_fmac_f32_e32 v83, 0, v92
	v_fmac_f32_e32 v85, v83, v96
	v_mul_f32_e32 v93, v85, v94
	v_pk_mul_f32 v[146:147], v[92:93], v[96:97]
	v_pk_add_f32 v[92:93], v[92:93], v[96:97]
	v_mov_b32_e32 v96, v95
	v_mov_b32_e32 v92, v146
	v_mov_b32_e32 v98, v95
	v_pk_mul_f32 v[146:147], v[146:147], v[94:95]
	v_pk_fma_f32 v[92:93], v[92:93], v[94:95], v[98:99]
	v_pk_mul_f32 v[96:97], v[146:147], v[96:97]
	s_nop 0
	v_mov_b32_e32 v97, v93
	ds_write_b64 v141, v[96:97] offset:52736

; DEVI unsigned pk2(float lo, float hi) { f32x2 v = {lo, hi}; bf16x2_t b = __builtin_convertvector(v, bf16x2_t); return __builtin_bit_cast(unsigned, b); }
; DEVI float bflo(unsigned u) { return __uint_as_float(u << 16); }
; DEVI float bfhi(unsigned u) { return __uint_as_float(u & 0xffff0000u); }
; template <bool PASS_C>
; DEVI void lru_item(const P& p, int item, int next_item, uint4& u0, uint4& u1, uint4& u2, float& cpre, char* smem) {
;     ...
;     {
;         const int tok = tid >> 2, cg0 = (tid & 3) * 16;
;         uint4 r[4][2];
; #pragma unroll
;         for (int k = 0; k < 4; ++k) { r[k][0] = *(const uint4*)(us + (tok + k) * 64 + cg0); r[k][1] = *(const uint4*)(us + (tok + k) * 64 + cg0 + 8); }
;         float val[16];
; #pragma unroll
;         for (int e = 0; e < 16; ++e) {
;             const int ch = cg0 + e;
;             float a = prm[4 * 64 + ch];
; #pragma unroll
;             for (int k = 0; k < 4; ++k) {
;                 const uint4 q = r[k][e >> 3];
;                 const unsigned wd = ((e >> 1) & 3) == 0 ? q.x : (((e >> 1) & 3) == 1 ? q.y : (((e >> 1) & 3) == 2 ? q.z : q.w));
;                 a += prm[k * 64 + ch] * ((e & 1) ? bfhi(wd) : bflo(wd));
;             }
;             val[e] = a;
;         }
;         uint4 o;
;         o.x = pk2(val[0], val[1]); o.y = pk2(val[2], val[3]); o.z = pk2(val[4], val[5]); o.w = pk2(val[6], val[7]);
;         *(uint4*)(ucb + tok * 128 + ((((cg0 >> 3) + 0) ^ (tok & 7)) << 4)) = o;
;         o.x = pk2(val[8], val[9]); o.y = pk2(val[10], val[11]); o.z = pk2(val[12], val[13]); o.w = pk2(val[14], val[15]);
;         *(uint4*)(ucb + tok * 128 + ((((cg0 >> 3) + 1) ^ (tok & 7)) << 4)) = o;
;     }
.LBB0_739:
	v_lshlrev_b64 v[106:107], 10, v[22:23]
	s_waitcnt lgkmcnt(0)
	s_barrier
	ds_read_b128 v[42:45], v127 offset:35840
	ds_read_b128 v[22:25], v127 offset:35856
	ds_read_b128 v[46:49], v127 offset:35968
	ds_read_b128 v[26:29], v127 offset:35984
	ds_read_b128 v[50:53], v127 offset:36096
	ds_read_b128 v[30:33], v127 offset:36112
	ds_read_b128 v[54:57], v127 offset:36224
	ds_read_b128 v[34:37], v127 offset:36240
	ds_read_b128 v[58:61], v117 offset:33792
	ds_read_b128 v[62:65], v117 offset:32768
	ds_read_b128 v[66:69], v117 offset:32784
	ds_read_b128 v[70:73], v117 offset:32800
	ds_read_b128 v[38:41], v117 offset:32816
	ds_read_b128 v[74:77], v117 offset:33024
	ds_read_b128 v[158:161], v117 offset:33808
	s_waitcnt lgkmcnt(14)
	v_lshlrev_b32_e32 v162, 16, v42
	v_and_b32_e32 v163, 0xffff0000, v42
	s_waitcnt lgkmcnt(5)
	v_pk_fma_f32 v[58:59], v[62:63], v[162:163], v[58:59]
	ds_read_b128 v[162:165], v117 offset:33280
	ds_read_b128 v[166:169], v117 offset:33536
	ds_read_b128 v[184:187], v117 offset:33040
	v_lshlrev_b32_e32 v42, 16, v43
	v_and_b32_e32 v43, 0xffff0000, v43
	v_lshlrev_b32_e32 v170, 16, v46
	v_and_b32_e32 v171, 0xffff0000, v46
	v_lshlrev_b32_e32 v46, 16, v47
	v_and_b32_e32 v47, 0xffff0000, v47
	v_pk_fma_f32 v[42:43], v[64:65], v[42:43], v[60:61]
	v_lshlrev_b32_e32 v192, 16, v50
	v_and_b32_e32 v193, 0xffff0000, v50
	s_waitcnt lgkmcnt(4)
	v_pk_fma_f32 v[58:59], v[74:75], v[170:171], v[58:59]
	ds_read_b128 v[188:191], v117 offset:33296
	v_lshlrev_b32_e32 v50, 16, v51
	v_and_b32_e32 v51, 0xffff0000, v51
	v_pk_fma_f32 v[42:43], v[76:77], v[46:47], v[42:43]
	v_lshlrev_b32_e32 v196, 16, v54
	v_and_b32_e32 v197, 0xffff0000, v54
	s_waitcnt lgkmcnt(3)
	v_pk_fma_f32 v[58:59], v[162:163], v[192:193], v[58:59]
	ds_read_b128 v[192:195], v117 offset:33552
	ds_read_b128 v[232:235], v117 offset:33824
	ds_read_b128 v[236:239], v117 offset:33056
	ds_read_b128 v[240:243], v117 offset:33840
	ds_read_b128 v[244:247], v117 offset:33312
	ds_read_b128 v[248:251], v117 offset:33568
	ds_read_b128 v[252:255], v117 offset:33072
	ds_read_b128 v[218:221], v117 offset:33328
	ds_read_b128 v[222:225], v117 offset:33584
	v_lshlrev_b32_e32 v54, 16, v55
	v_and_b32_e32 v55, 0xffff0000, v55
	v_pk_fma_f32 v[42:43], v[164:165], v[50:51], v[42:43]
	v_lshlrev_b32_e32 v46, 16, v48
	s_waitcnt lgkmcnt(11)
	v_pk_fma_f32 v[164:165], v[168:169], v[54:55], v[42:43]
	v_lshlrev_b32_e32 v42, 16, v44
	v_and_b32_e32 v43, 0xffff0000, v44
	v_and_b32_e32 v47, 0xffff0000, v48
	v_pk_fma_f32 v[42:43], v[66:67], v[42:43], v[158:159]
	v_lshlrev_b32_e32 v50, 16, v52
	v_and_b32_e32 v51, 0xffff0000, v52
	s_waitcnt lgkmcnt(10)
	v_pk_fma_f32 v[42:43], v[184:185], v[46:47], v[42:43]
	v_lshlrev_b32_e32 v54, 16, v56
	v_and_b32_e32 v55, 0xffff0000, v56
	s_waitcnt lgkmcnt(9)
	v_pk_fma_f32 v[42:43], v[188:189], v[50:51], v[42:43]
	v_lshlrev_b32_e32 v44, 16, v49
	s_waitcnt lgkmcnt(8)
	v_pk_fma_f32 v[158:159], v[192:193], v[54:55], v[42:43]
	v_lshlrev_b32_e32 v42, 16, v45
	v_and_b32_e32 v43, 0xffff0000, v45
	v_and_b32_e32 v45, 0xffff0000, v49
	v_pk_fma_f32 v[42:43], v[68:69], v[42:43], v[160:161]
	v_lshlrev_b32_e32 v46, 16, v53
	v_and_b32_e32 v47, 0xffff0000, v53
	v_pk_fma_f32 v[42:43], v[186:187], v[44:45], v[42:43]
	v_lshlrev_b32_e32 v48, 16, v57
	v_and_b32_e32 v49, 0xffff0000, v57
	v_pk_fma_f32 v[42:43], v[190:191], v[46:47], v[42:43]
	v_lshlrev_b32_e32 v54, 16, v22
	v_pk_fma_f32 v[160:161], v[194:195], v[48:49], v[42:43]
	v_and_b32_e32 v55, 0xffff0000, v22
	v_pk_fma_f32 v[162:163], v[166:167], v[196:197], v[58:59]
	v_lshlrev_b32_e32 v22, 16, v23
	s_waitcnt lgkmcnt(7)
	v_pk_fma_f32 v[42:43], v[70:71], v[54:55], v[232:233]
	v_and_b32_e32 v23, 0xffff0000, v23
	v_lshlrev_b32_e32 v66, 16, v26
	v_and_b32_e32 v67, 0xffff0000, v26
	v_lshlrev_b32_e32 v26, 16, v27
	v_and_b32_e32 v27, 0xffff0000, v27
	v_pk_fma_f32 v[22:23], v[72:73], v[22:23], v[234:235]
	v_lshlrev_b32_e32 v74, 16, v30
	v_and_b32_e32 v75, 0xffff0000, v30
	s_waitcnt lgkmcnt(6)
	v_pk_fma_f32 v[42:43], v[236:237], v[66:67], v[42:43]
	v_lshlrev_b32_e32 v30, 16, v31
	v_and_b32_e32 v31, 0xffff0000, v31
	v_pk_fma_f32 v[22:23], v[238:239], v[26:27], v[22:23]
	v_lshlrev_b32_e32 v166, 16, v34
	v_and_b32_e32 v167, 0xffff0000, v34
	s_waitcnt lgkmcnt(4)
	v_pk_fma_f32 v[42:43], v[244:245], v[74:75], v[42:43]
	v_lshlrev_b32_e32 v34, 16, v35
	v_and_b32_e32 v35, 0xffff0000, v35
	v_pk_fma_f32 v[22:23], v[246:247], v[30:31], v[22:23]
	v_lshlrev_b32_e32 v30, 16, v28
	s_waitcnt lgkmcnt(3)
	v_pk_fma_f32 v[26:27], v[250:251], v[34:35], v[22:23]
	v_lshlrev_b32_e32 v22, 16, v24
	v_and_b32_e32 v23, 0xffff0000, v24
	v_and_b32_e32 v31, 0xffff0000, v28
	v_pk_fma_f32 v[22:23], v[38:39], v[22:23], v[240:241]
	v_lshlrev_b32_e32 v34, 16, v32
	v_and_b32_e32 v35, 0xffff0000, v32
	s_waitcnt lgkmcnt(2)
	v_pk_fma_f32 v[22:23], v[252:253], v[30:31], v[22:23]
	v_lshlrev_b32_e32 v44, 16, v36
	v_and_b32_e32 v45, 0xffff0000, v36
	s_waitcnt lgkmcnt(1)
	v_pk_fma_f32 v[22:23], v[218:219], v[34:35], v[22:23]
	v_lshlrev_b32_e32 v24, 16, v29
	s_waitcnt lgkmcnt(0)
	v_pk_fma_f32 v[30:31], v[222:223], v[44:45], v[22:23]
	v_lshlrev_b32_e32 v22, 16, v25
	v_and_b32_e32 v23, 0xffff0000, v25
	v_and_b32_e32 v25, 0xffff0000, v29
	v_pk_fma_f32 v[22:23], v[40:41], v[22:23], v[242:243]
	v_lshlrev_b32_e32 v28, 16, v33
	v_and_b32_e32 v29, 0xffff0000, v33
	v_pk_fma_f32 v[22:23], v[254:255], v[24:25], v[22:23]
	v_lshlrev_b32_e32 v32, 16, v37
	v_and_b32_e32 v33, 0xffff0000, v37
	v_pk_fma_f32 v[22:23], v[220:221], v[28:29], v[22:23]
	v_pk_fma_f32 v[42:43], v[248:249], v[166:167], v[42:43]
	v_pk_fma_f32 v[28:29], v[224:225], v[32:33], v[22:23]
	v_cvt_pk_bf16_f32 v22, v162, v163
	v_cvt_pk_bf16_f32 v23, v164, v165
	v_cvt_pk_bf16_f32 v24, v158, v159
	v_cvt_pk_bf16_f32 v25, v160, v161
	ds_write_b128 v128, v[22:25] offset:44544
	v_cvt_pk_bf16_f32 v22, v42, v43
	v_cvt_pk_bf16_f32 v23, v26, v27
	v_cvt_pk_bf16_f32 v24, v30, v31
	v_cvt_pk_bf16_f32 v25, v28, v29
	ds_write_b128 v129, v[22:25] offset:44544
	v_add_u32_e32 v22, v119, v120
	s_waitcnt lgkmcnt(0)
	s_barrier
; DEVI float bf2f(bf16_t h) { return __uint_as_float(((unsigned)h) << 16); }
; template <bool PASS_C>
; DEVI void lru_item(const P& p, int item, int next_item, uint4& u0, uint4& u1, uint4& u2, float& cpre, char* smem) {
;     ...
;     f32x4 acc[16];
; #pragma unroll
;     for (int n = 0; n < 16; ++n) acc[n] = (f32x4){0.f, 0.f, 0.f, 0.f};
;     {
;         bf16x8 af[2];
; #pragma unroll
;         for (int kk = 0; kk < 2; ++kk) af[kk] = *(const bf16x8*)(ucb + (16 * w + fr) * 128 + (((kk * 4 + fq) ^ (fr & 7)) << 4));
; #pragma unroll
;         for (int n = 0; n < 16; ++n)
; #pragma unroll
;             for (int kk = 0; kk < 2; ++kk) {
;                 const bf16x8 bfr = *(const bf16x8*)(smem + (16 * n + fr) * 128 + (((kk * 4 + fq) ^ (fr & 7)) << 4));
;                 acc[n] = __builtin_amdgcn_mfma_f32_16x16x32_bf16(af[kk], bfr, acc[n], 0, 0, 0);
;             }
;     }
;     float av[4][2][4], bv[4][2][4], apre[4][2], bpre[4][2];
; #pragma unroll
;     for (int nn = 0; nn < 4; ++nn) {
;         const int ch = 16 * nn + fr;
;         float uc[4];
; #pragma unroll
;         for (int j = 0; j < 4; ++j) {
;             const int tl = 16 * w + 4 * fq + j;
;             uc[j] = bf2f(*(const bf16_t*)(ucb + tl * 128 + ((((ch >> 3)) ^ (tl & 7)) << 4) + (ch & 7) * 2));
;         }
; #pragma unroll
;         for (int d = 0; d < 2; ++d) {
;             const float ba = prm[(5 + d) * 64 + ch], bx = prm[(7 + d) * 64 + ch], nsp8 = prm[(9 + d) * 64 + ch];
; #pragma unroll
;             for (int j = 0; j < 4; ++j) {
;                 const float r = __builtin_amdgcn_rcpf(1.0f + __builtin_amdgcn_exp2f(__builtin_fmaf(acc[(2 * d) * 4 + nn][j], -LOG2E, ba)));
;                 const float ig = __builtin_amdgcn_rcpf(1.0f + __builtin_amdgcn_exp2f(__builtin_fmaf(acc[(2 * d + 1) * 4 + nn][j], -LOG2E, bx)));
;                 const float a_ = __builtin_amdgcn_exp2f(nsp8 * r);
;                 av[nn][d][j] = a_;
;                 bv[nn][d][j] = __builtin_amdgcn_sqrtf(__builtin_fmaf(-a_, a_, 1.0f)) * ig * uc[j];
	v_add_u32_e32 v87, v118, v120
	v_add_u32_e32 v30, v119, v121
	v_add_u32_e32 v89, v118, v121
	ds_read_b128 v[26:29], v22 offset:44544
	ds_read_b128 v[158:161], v30 offset:44544
	ds_read_b32 v93, v122 offset:35072
	ds_read_b128 v[232:235], v87
	ds_read_b128 v[236:239], v89
	ds_read_b128 v[240:243], v87 offset:2048
	ds_read_b128 v[244:247], v89 offset:2048
	ds_read_b128 v[248:251], v87 offset:4096
	ds_read_b128 v[192:195], v89 offset:4096
	ds_read_b128 v[252:255], v87 offset:6144
	ds_read_b128 v[218:221], v89 offset:6144
	s_waitcnt lgkmcnt(4)
	v_mfma_f32_16x16x32_bf16 v[166:169], v[26:29], v[232:235], 0
	ds_read_b128 v[222:225], v87 offset:8192
	ds_read_b128 v[226:229], v89 offset:8192
	ds_read_b128 v[162:165], v87 offset:10240
	ds_read_b128 v[188:191], v89 offset:10240
	v_mfma_f32_16x16x32_bf16 v[62:65], v[26:29], v[240:243], 0
	v_mfma_f32_16x16x32_bf16 v[166:169], v[158:161], v[236:239], v[166:169]
	v_mfma_f32_16x16x32_bf16 v[62:65], v[158:161], v[244:247], v[62:65]
	s_waitcnt lgkmcnt(4)
	v_mfma_f32_16x16x32_bf16 v[46:49], v[26:29], v[248:251], 0
	ds_read_b128 v[232:235], v87 offset:12288
	ds_read_b128 v[236:239], v89 offset:12288
	ds_read_b128 v[240:243], v87 offset:14336
	ds_read_b128 v[244:247], v89 offset:14336
	v_mfma_f32_16x16x32_bf16 v[30:33], v[26:29], v[252:255], 0
	v_mfma_f32_16x16x32_bf16 v[46:49], v[158:161], v[192:195], v[46:49]
	v_mfma_f32_16x16x32_bf16 v[30:33], v[158:161], v[218:221], v[30:33]
	s_waitcnt lgkmcnt(4)
	v_mfma_f32_16x16x32_bf16 v[184:187], v[26:29], v[222:225], 0
	ds_read_b128 v[248:251], v87 offset:16384
	ds_read_b128 v[192:195], v89 offset:16384
	ds_read_b128 v[252:255], v87 offset:18432
	ds_read_b128 v[218:221], v89 offset:18432
	v_mfma_f32_16x16x32_bf16 v[66:69], v[26:29], v[162:165], 0
	v_mfma_f32_16x16x32_bf16 v[184:187], v[158:161], v[226:229], v[184:187]
	v_mfma_f32_16x16x32_bf16 v[66:69], v[158:161], v[188:191], v[66:69]
	s_waitcnt lgkmcnt(4)
	v_mfma_f32_16x16x32_bf16 v[50:53], v[26:29], v[232:235], 0
	ds_read_b128 v[222:225], v87 offset:20480
	ds_read_b128 v[226:229], v89 offset:20480
	ds_read_b128 v[162:165], v87 offset:22528
	ds_read_b128 v[188:191], v89 offset:22528
	v_mfma_f32_16x16x32_bf16 v[34:37], v[26:29], v[240:243], 0
	v_mfma_f32_16x16x32_bf16 v[50:53], v[158:161], v[236:239], v[50:53]
	v_mfma_f32_16x16x32_bf16 v[34:37], v[158:161], v[244:247], v[34:37]
	s_waitcnt lgkmcnt(4)
	v_mfma_f32_16x16x32_bf16 v[70:73], v[26:29], v[248:251], 0
	ds_read_b128 v[232:235], v87 offset:24576
	ds_read_b128 v[236:239], v89 offset:24576
	ds_read_b128 v[240:243], v87 offset:26624
	ds_read_b128 v[244:247], v89 offset:26624
	v_mfma_f32_16x16x32_bf16 v[54:57], v[26:29], v[252:255], 0
	v_mfma_f32_16x16x32_bf16 v[70:73], v[158:161], v[192:195], v[70:73]
	v_mfma_f32_16x16x32_bf16 v[54:57], v[158:161], v[218:221], v[54:57]
	s_waitcnt lgkmcnt(4)
	v_mfma_f32_16x16x32_bf16 v[38:41], v[26:29], v[222:225], 0
	ds_read_b128 v[248:251], v87 offset:28672
	ds_read_b128 v[252:255], v87 offset:30720
	ds_read_b128 v[192:195], v89 offset:28672
	v_mfma_f32_16x16x32_bf16 v[22:25], v[26:29], v[162:165], 0
	v_mfma_f32_16x16x32_bf16 v[38:41], v[158:161], v[226:229], v[38:41]
	v_mfma_f32_16x16x32_bf16 v[22:25], v[158:161], v[188:191], v[22:25]
	s_waitcnt lgkmcnt(3)
	v_mfma_f32_16x16x32_bf16 v[74:77], v[26:29], v[232:235], 0
	v_mfma_f32_16x16x32_bf16 v[58:61], v[26:29], v[240:243], 0
	v_mfma_f32_16x16x32_bf16 v[74:77], v[158:161], v[236:239], v[74:77]
	v_mfma_f32_16x16x32_bf16 v[58:61], v[158:161], v[244:247], v[58:61]
	s_waitcnt lgkmcnt(1)
	v_mfma_f32_16x16x32_bf16 v[42:45], v[26:29], v[248:251], 0
	v_mfma_f32_16x16x32_bf16 v[26:29], v[26:29], v[252:255], 0
	ds_read_b128 v[162:165], v89 offset:30720
	ds_read2st64_b32 v[170:171], v122 offset0:133 offset1:135
	ds_read_u16 v246, v130 offset:44544
	ds_read_u16 v247, v131 offset:44544
	ds_read_u16 v248, v132 offset:44544
	ds_read_u16 v249, v133 offset:44544
	ds_read2st64_b32 v[232:233], v122 offset0:134 offset1:136
	ds_read_b32 v250, v122 offset:35328
	v_add_u32_e32 v217, 64, v122
	ds_read2st64_b32 v[234:235], v217 offset0:133 offset1:135
	ds_read_u16 v251, v134 offset:44544
	ds_read_u16 v252, v135 offset:44544
	ds_read_u16 v253, v136 offset:44544
	ds_read_u16 v254, v137 offset:44544
	ds_read_b32 v255, v122 offset:35136
	v_add_u32_e32 v217, 64, v122
	ds_read2st64_b32 v[236:237], v217 offset0:134 offset1:136
	ds_read_b32 v218, v122 offset:35392
	v_add_u32_e32 v217, 0x80, v122
	ds_read2st64_b32 v[238:239], v217 offset0:133 offset1:135
	ds_read_u16 v219, v138 offset:44544
	ds_read_u16 v220, v139 offset:44544
	ds_read_u16 v221, v140 offset:44544
	ds_read_u16 v222, v141 offset:44544
	ds_read_b32 v223, v122 offset:35200
	v_add_u32_e32 v217, 0x80, v122
	ds_read2st64_b32 v[240:241], v217 offset0:134 offset1:136
	ds_read_b32 v224, v122 offset:35456
	v_add_u32_e32 v217, 0xc0, v122
	ds_read2st64_b32 v[242:243], v217 offset0:133 offset1:135
	ds_read_u16 v225, v142 offset:44544
	ds_read_u16 v226, v143 offset:44544
	ds_read_u16 v227, v144 offset:44544
	ds_read_u16 v228, v145 offset:44544
	ds_read_b32 v229, v122 offset:35264
	v_add_u32_e32 v217, 0xc0, v122
	ds_read2st64_b32 v[244:245], v217 offset0:134 offset1:136
	ds_read_b32 v231, v122 offset:35520
	s_waitcnt lgkmcnt(0)
; template <bool PASS_C>
; DEVI void lru_item(const P& p, int item, int next_item, uint4& u0, uint4& u1, uint4& u2, float& cpre, char* smem) {
;     ...
;         for (int d = 0; d < 2; ++d) {
;             const float ba = prm[(5 + d) * 64 + ch], bx = prm[(7 + d) * 64 + ch], nsp8 = prm[(9 + d) * 64 + ch];
; #pragma unroll
;             for (int j = 0; j < 4; ++j) {
;                 const float r = __builtin_amdgcn_rcpf(1.0f + __builtin_amdgcn_exp2f(__builtin_fmaf(acc[(2 * d) * 4 + nn][j], -LOG2E, ba)));
;                 const float ig = __builtin_amdgcn_rcpf(1.0f + __builtin_amdgcn_exp2f(__builtin_fmaf(acc[(2 * d + 1) * 4 + nn][j], -LOG2E, bx)));
;                 const float a_ = __builtin_amdgcn_exp2f(nsp8 * r);
;                 av[nn][d][j] = a_;
;                 bv[nn][d][j] = __builtin_amdgcn_sqrtf(__builtin_fmaf(-a_, a_, 1.0f)) * ig * uc[j];
;             }
;             float A = 1.f, Bq = 0.f;
;             if (d == 0) {
; #pragma unroll
;                 for (int j = 0; j < 4; ++j) { Bq = av[nn][d][j] * Bq + bv[nn][d][j]; A *= av[nn][d][j]; }
;             } else {
; #pragma unroll
;                 for (int j = 3; j >= 0; --j) { Bq = av[nn][d][j] * Bq + bv[nn][d][j]; A *= av[nn][d][j]; }
;             }
;             float Ag[4], Bg[4];
;             rowgather4(A, Ag); rowgather4(Bq, Bg);
;             float AW = 1.f, BW = 0.f, AP = 1.f, BP = 0.f;
;             if (d == 0) {
; #pragma unroll
;                 for (int g = 0; g < 4; ++g) {
;                     if (g == fq) { AP = AW; BP = BW; }
;                     BW = Ag[g] * BW + Bg[g]; AW *= Ag[g];
;                 }
;             } else {
; #pragma unroll
;                 for (int g = 3; g >= 0; --g) {
;                     if (g == fq) { AP = AW; BP = BW; }
;                     BW = Ag[g] * BW + Bg[g]; AW *= Ag[g];
;                 }
;             }
;             apre[nn][d] = AP; bpre[nn][d] = BP;
;             if (fq == 0) { wagg[((w * 2 + d) * 64 + ch) * 2 + 0] = AW; wagg[((w * 2 + d) * 64 + ch) * 2 + 1] = BW; }
;         }
	v_fmamk_f32 v95, v166, 0xbfb8aa3b, v170
	v_exp_f32_e32 v95, v95
	v_mfma_f32_16x16x32_bf16 v[42:45], v[158:161], v[192:195], v[42:45]
	v_fmamk_f32 v99, v168, 0xbfb8aa3b, v170
	v_fmamk_f32 v101, v186, 0xbfb8aa3b, v171
	v_exp_f32_e32 v99, v99
	v_mfma_f32_16x16x32_bf16 v[26:29], v[158:161], v[162:165], v[26:29]
	v_lshlrev_b32_e32 v164, 16, v246
	v_lshlrev_b32_e32 v161, 16, v247
	v_add_f32_e32 v87, 1.0, v95
	v_fmamk_f32 v89, v184, 0xbfb8aa3b, v171
	v_exp_f32_e32 v89, v89
	v_rcp_f32_e32 v87, v87
	v_lshlrev_b32_e32 v162, 16, v248
	v_add_f32_e32 v95, 1.0, v89
	v_mul_f32_e32 v87, v93, v87
	v_exp_f32_e32 v89, v87
	v_rcp_f32_e32 v87, v95
	v_fmamk_f32 v95, v167, 0xbfb8aa3b, v170
	v_exp_f32_e32 v95, v95
	v_lshlrev_b32_e32 v163, 16, v249
	v_fma_f32 v97, -v89, v89, 1.0
	v_sqrt_f32_e32 v97, v97
	v_add_f32_e32 v91, 1.0, v95
	v_rcp_f32_e32 v91, v91
	v_fmamk_f32 v95, v185, 0xbfb8aa3b, v171
	v_exp_f32_e32 v95, v95
	v_mul_f32_e32 v87, v87, v97
	v_mul_f32_e32 v91, v93, v91
	v_exp_f32_e32 v91, v91
	v_add_f32_e32 v95, 1.0, v95
	v_rcp_f32_e32 v95, v95
	v_exp_f32_e32 v101, v101
	v_fma_f32 v97, -v91, v91, 1.0
	v_sqrt_f32_e32 v97, v97
	v_fmamk_f32 v171, v187, 0xbfb8aa3b, v171
	v_exp_f32_e32 v105, v171
	v_mul_f32_e32 v87, v87, v164
	v_mul_f32_e32 v97, v95, v97
	v_add_f32_e32 v95, 1.0, v99
	v_add_f32_e32 v99, 1.0, v101
	v_fmamk_f32 v101, v169, 0xbfb8aa3b, v170
	v_exp_f32_e32 v101, v101
	v_rcp_f32_e32 v95, v95
	v_rcp_f32_e32 v99, v99
	v_add_f32_e32 v101, 1.0, v101
	v_rcp_f32_e32 v101, v101
	v_mul_f32_e32 v95, v93, v95
	v_exp_f32_e32 v95, v95
	v_mul_f32_e32 v93, v93, v101
	v_exp_f32_e32 v101, v93
	v_add_f32_e32 v93, 1.0, v105
	v_fma_f32 v103, -v95, v95, 1.0
	v_rcp_f32_e32 v105, v93
	v_fma_f32 v93, -v101, v101, 1.0
	v_sqrt_f32_e32 v103, v103
	v_sqrt_f32_e32 v157, v93
	v_mul_f32_e32 v93, v97, v161
	v_mul_f32_e32 v97, v99, v103
	v_mul_f32_e32 v99, v105, v157
	v_fma_f32 v105, 0, v89, v87
	v_mul_f32_e32 v97, v97, v162
	v_mul_f32_e32 v103, v89, v91
	v_fma_f32 v105, v91, v105, v93
	v_mul_f32_e32 v99, v99, v163
	v_mul_f32_e32 v103, v95, v103
	v_fma_f32 v105, v95, v105, v97
	v_mul_f32_e32 v103, v101, v103
	v_fma_f32 v105, v101, v105, v99
	v_mov_b32_e32 v159, v103
	v_mov_b32_e32 v157, v105
	s_nop 0
	v_permlane16_swap_b32_e32 v103, v159
	v_permlane16_swap_b32_e32 v105, v157
	v_mov_b32_e32 v160, v103
	v_mov_b32_e32 v158, v105
	s_nop 0
	v_permlane32_swap_b32_e32 v103, v160
	v_mov_b32_e32 v165, v159
	v_permlane32_swap_b32_e32 v105, v158
	v_mov_b32_e32 v166, v157
	v_permlane32_swap_b32_e32 v159, v165
	s_nop 0
	v_permlane32_swap_b32_e32 v157, v166
	v_fmac_f32_e32 v105, 0, v103
	v_fmac_f32_e32 v157, v105, v159
	v_mul_f32_e32 v159, v103, v159
	v_fmac_f32_e32 v158, v157, v160
	v_mul_f32_e32 v160, v159, v160
	s_and_saveexec_b64 s[28:29], s[10:11]
	v_mul_f32_e32 v167, v158, v165
	v_mul_f32_e32 v168, v160, v165
	v_add_f32_e32 v169, v167, v166
	ds_write_b64 v149, v[168:169] offset:52736
	s_or_b64 exec, exec, s[28:29]
	v_fmamk_f32 v70, v70, 0xbfb8aa3b, v232
	v_exp_f32_e32 v70, v70
	v_fmamk_f32 v71, v71, 0xbfb8aa3b, v232
	v_exp_f32_e32 v71, v71
	v_fmamk_f32 v74, v74, 0xbfb8aa3b, v233
	v_add_f32_e32 v70, 1.0, v70
	v_rcp_f32_e32 v70, v70
	v_add_f32_e32 v71, 1.0, v71
	v_exp_f32_e32 v74, v74
	v_rcp_f32_e32 v71, v71
	v_mul_f32_e32 v70, v250, v70
	v_exp_f32_e32 v70, v70
	v_fmamk_f32 v75, v75, 0xbfb8aa3b, v233
	v_add_f32_e32 v74, 1.0, v74
	v_mul_f32_e32 v71, v250, v71
	v_fma_f32 v168, -v70, v70, 1.0
	v_fmamk_f32 v72, v72, 0xbfb8aa3b, v232
	v_fmamk_f32 v73, v73, 0xbfb8aa3b, v232
	v_exp_f32_e32 v75, v75
	v_rcp_f32_e32 v74, v74
	v_exp_f32_e32 v71, v71
	v_sqrt_f32_e32 v168, v168
	v_exp_f32_e32 v72, v72
	v_exp_f32_e32 v73, v73
	v_add_f32_e32 v75, 1.0, v75
	v_fma_f32 v169, -v71, v71, 1.0
	v_mul_f32_e32 v74, v74, v168
	v_fmamk_f32 v76, v76, 0xbfb8aa3b, v233
	v_add_f32_e32 v72, 1.0, v72
	v_add_f32_e32 v73, 1.0, v73
	v_rcp_f32_e32 v75, v75
	v_mul_f32_e32 v74, v74, v164
	v_sqrt_f32_e32 v164, v169
	v_exp_f32_e32 v76, v76
	v_rcp_f32_e32 v72, v72
	v_rcp_f32_e32 v73, v73
	v_fmamk_f32 v167, v77, 0xbfb8aa3b, v233
	v_mul_f32_e32 v164, v75, v164
	v_add_f32_e32 v75, 1.0, v76
	v_mul_f32_e32 v72, v250, v72
	v_exp_f32_e32 v77, v167
	v_mul_f32_e32 v73, v250, v73
	v_exp_f32_e32 v72, v72
	v_rcp_f32_e32 v76, v75
	v_exp_f32_e32 v75, v73
	v_add_f32_e32 v73, 1.0, v77
	v_fma_f32 v166, -v72, v72, 1.0
	v_rcp_f32_e32 v77, v73
	v_fma_f32 v73, -v75, v75, 1.0
	v_sqrt_f32_e32 v165, v166
	v_sqrt_f32_e32 v166, v73
	v_mul_f32_e32 v73, v164, v161
	v_mul_f32_e32 v161, v75, v72
	v_mul_f32_e32 v76, v76, v165
	v_mul_f32_e32 v77, v77, v166
	v_mul_f32_e32 v77, v77, v163
	v_mul_f32_e32 v161, v71, v161
	v_mul_f32_e32 v76, v76, v162
	v_mul_f32_e32 v165, v70, v161
	v_fma_f32 v161, 0, v75, v77
	v_fma_f32 v161, v72, v161, v76
	v_fma_f32 v161, v71, v161, v73
	v_fma_f32 v168, v70, v161, v74
	v_mov_b32_e32 v167, v165
	v_mov_b32_e32 v161, v168
	s_nop 0
	v_permlane16_swap_b32_e32 v165, v167
	v_permlane16_swap_b32_e32 v168, v161
	v_mov_b32_e32 v162, v167
	v_mov_b32_e32 v164, v161
	v_mov_b32_e32 v166, v165
	v_permlane32_swap_b32_e32 v167, v162
	v_mov_b32_e32 v163, v168
	v_permlane32_swap_b32_e32 v161, v164
	v_permlane32_swap_b32_e32 v165, v166
	v_permlane32_swap_b32_e32 v168, v163
	v_fmac_f32_e32 v164, 0, v162
	v_fmac_f32_e32 v163, v164, v166
	v_mul_f32_e32 v166, v166, v162
	v_fmac_f32_e32 v161, v163, v167
	v_mul_f32_e32 v167, v166, v167
	s_and_saveexec_b64 s[28:29], s[10:11]
	v_mul_f32_e32 v169, v161, v165
	v_mul_f32_e32 v170, v167, v165
	v_add_f32_e32 v171, v169, v168
	ds_write_b64 v149, v[170:171] offset:53248
	s_or_b64 exec, exec, s[28:29]
	v_lshlrev_b32_e32 v185, 16, v251
	v_lshlrev_b32_e32 v183, 16, v252
	v_lshlrev_b32_e32 v177, 16, v253
; template <bool PASS_C>
; DEVI void lru_item(const P& p, int item, int next_item, uint4& u0, uint4& u1, uint4& u2, float& cpre, char* smem) {
;     ...
;         for (int d = 0; d < 2; ++d) {
;             const float ba = prm[(5 + d) * 64 + ch], bx = prm[(7 + d) * 64 + ch], nsp8 = prm[(9 + d) * 64 + ch];
; #pragma unroll
;             for (int j = 0; j < 4; ++j) {
;                 const float r = __builtin_amdgcn_rcpf(1.0f + __builtin_amdgcn_exp2f(__builtin_fmaf(acc[(2 * d) * 4 + nn][j], -LOG2E, ba)));
;                 const float ig = __builtin_amdgcn_rcpf(1.0f + __builtin_amdgcn_exp2f(__builtin_fmaf(acc[(2 * d + 1) * 4 + nn][j], -LOG2E, bx)));
;                 const float a_ = __builtin_amdgcn_exp2f(nsp8 * r);
;                 av[nn][d][j] = a_;
;                 bv[nn][d][j] = __builtin_amdgcn_sqrtf(__builtin_fmaf(-a_, a_, 1.0f)) * ig * uc[j];
;             }
;             float A = 1.f, Bq = 0.f;
;             if (d == 0) {
; #pragma unroll
;                 for (int j = 0; j < 4; ++j) { Bq = av[nn][d][j] * Bq + bv[nn][d][j]; A *= av[nn][d][j]; }
;             } else {
; #pragma unroll
;                 for (int j = 3; j >= 0; --j) { Bq = av[nn][d][j] * Bq + bv[nn][d][j]; A *= av[nn][d][j]; }
;             }
;             float Ag[4], Bg[4];
;             rowgather4(A, Ag); rowgather4(Bq, Bg);
;             float AW = 1.f, BW = 0.f, AP = 1.f, BP = 0.f;
;             if (d == 0) {
; #pragma unroll
;                 for (int g = 0; g < 4; ++g) {
;                     if (g == fq) { AP = AW; BP = BW; }
;                     BW = Ag[g] * BW + Bg[g]; AW *= Ag[g];
;                 }
;             } else {
; #pragma unroll
;                 for (int g = 3; g >= 0; --g) {
;                     if (g == fq) { AP = AW; BP = BW; }
;                     BW = Ag[g] * BW + Bg[g]; AW *= Ag[g];
;                 }
;             }
;             apre[nn][d] = AP; bpre[nn][d] = BP;
;             if (fq == 0) { wagg[((w * 2 + d) * 64 + ch) * 2 + 0] = AW; wagg[((w * 2 + d) * 64 + ch) * 2 + 1] = BW; }
;         }
	v_fmamk_f32 v62, v62, 0xbfb8aa3b, v234
	v_exp_f32_e32 v62, v62
	v_fmamk_f32 v63, v63, 0xbfb8aa3b, v234
	v_fmamk_f32 v66, v66, 0xbfb8aa3b, v235
	v_exp_f32_e32 v63, v63
	v_add_f32_e32 v62, 1.0, v62
	v_rcp_f32_e32 v62, v62
	v_exp_f32_e32 v66, v66
	v_add_f32_e32 v63, 1.0, v63
	v_rcp_f32_e32 v63, v63
	v_mul_f32_e32 v62, v255, v62
	v_add_f32_e32 v165, 1.0, v66
	v_exp_f32_e32 v66, v62
	v_rcp_f32_e32 v62, v165
	v_fmamk_f32 v67, v67, 0xbfb8aa3b, v235
	v_mul_f32_e32 v63, v255, v63
	v_fma_f32 v165, -v66, v66, 1.0
	v_sqrt_f32_e32 v165, v165
	v_exp_f32_e32 v67, v67
	v_exp_f32_e32 v63, v63
	v_fmamk_f32 v64, v64, 0xbfb8aa3b, v234
	v_exp_f32_e32 v64, v64
	v_mul_f32_e32 v62, v62, v165
	v_add_f32_e32 v67, 1.0, v67
	v_fma_f32 v165, -v63, v63, 1.0
	v_rcp_f32_e32 v67, v67
	v_sqrt_f32_e32 v165, v165
	v_add_f32_e32 v64, 1.0, v64
	v_rcp_f32_e32 v64, v64
	v_fmamk_f32 v65, v65, 0xbfb8aa3b, v234
	v_mul_f32_e32 v67, v67, v165
	v_exp_f32_e32 v165, v65
	v_mul_f32_e32 v64, v255, v64
	v_exp_f32_e32 v65, v64
	v_fmamk_f32 v68, v68, 0xbfb8aa3b, v235
	v_add_f32_e32 v64, 1.0, v165
	v_rcp_f32_e32 v64, v64
	v_fmamk_f32 v169, v69, 0xbfb8aa3b, v235
	v_exp_f32_e32 v168, v169
	v_exp_f32_e32 v68, v68
	v_mul_f32_e32 v64, v255, v64
	v_exp_f32_e32 v69, v64
	v_add_f32_e32 v64, 1.0, v168
	v_add_f32_e32 v68, 1.0, v68
	v_fma_f32 v165, -v65, v65, 1.0
	v_rcp_f32_e32 v168, v64
	v_fma_f32 v64, -v69, v69, 1.0
	v_rcp_f32_e32 v68, v68
	v_sqrt_f32_e32 v165, v165
	v_sqrt_f32_e32 v169, v64
	v_mul_f32_e32 v62, v62, v185
	v_mul_f32_e32 v64, v67, v183
	v_mul_f32_e32 v67, v68, v165
	v_mul_f32_e32 v68, v168, v169
	v_fma_f32 v168, 0, v66, v62
	v_lshlrev_b32_e32 v184, 16, v254
	v_mul_f32_e32 v67, v67, v177
	v_mul_f32_e32 v165, v66, v63
	v_fma_f32 v168, v63, v168, v64
	v_mul_f32_e32 v68, v68, v184
	v_mul_f32_e32 v165, v65, v165
	v_fma_f32 v168, v65, v168, v67
	v_mul_f32_e32 v165, v69, v165
	v_fma_f32 v168, v69, v168, v68
	v_mov_b32_e32 v171, v165
	v_mov_b32_e32 v169, v168
	s_nop 0
	v_permlane16_swap_b32_e32 v165, v171
	v_permlane16_swap_b32_e32 v168, v169
	v_mov_b32_e32 v173, v165
	v_mov_b32_e32 v170, v168
	s_nop 0
	v_permlane32_swap_b32_e32 v165, v173
	v_mov_b32_e32 v187, v171
	v_permlane32_swap_b32_e32 v168, v170
	v_mov_b32_e32 v188, v169
	v_permlane32_swap_b32_e32 v171, v187
	s_nop 0
	v_permlane32_swap_b32_e32 v169, v188
	v_fmac_f32_e32 v168, 0, v165
	v_fmac_f32_e32 v169, v168, v171
	v_mul_f32_e32 v171, v165, v171
	v_fmac_f32_e32 v170, v169, v173
	v_mul_f32_e32 v173, v171, v173
	s_and_saveexec_b64 s[28:29], s[10:11]
	v_mul_f32_e32 v189, v170, v187
	v_mul_f32_e32 v190, v173, v187
	v_add_f32_e32 v191, v189, v188
	ds_write_b64 v150, v[190:191] offset:52736
	s_or_b64 exec, exec, s[28:29]
	v_fmamk_f32 v54, v54, 0xbfb8aa3b, v236
	v_exp_f32_e32 v54, v54
	v_fmamk_f32 v55, v55, 0xbfb8aa3b, v236
	v_exp_f32_e32 v55, v55
	v_fmamk_f32 v58, v58, 0xbfb8aa3b, v237
	v_add_f32_e32 v54, 1.0, v54
	v_rcp_f32_e32 v54, v54
	v_add_f32_e32 v55, 1.0, v55
	v_exp_f32_e32 v58, v58
	v_rcp_f32_e32 v55, v55
	v_mul_f32_e32 v54, v218, v54
	v_exp_f32_e32 v54, v54
	v_fmamk_f32 v56, v56, 0xbfb8aa3b, v236
	v_fmamk_f32 v59, v59, 0xbfb8aa3b, v237
	v_add_f32_e32 v58, 1.0, v58
	v_mul_f32_e32 v55, v218, v55
	v_fma_f32 v189, -v54, v54, 1.0
	v_exp_f32_e32 v56, v56
	v_fmamk_f32 v57, v57, 0xbfb8aa3b, v236
	v_exp_f32_e32 v59, v59
	v_rcp_f32_e32 v58, v58
	v_exp_f32_e32 v55, v55
	v_sqrt_f32_e32 v189, v189
	v_exp_f32_e32 v57, v57
	v_add_f32_e32 v56, 1.0, v56
	v_add_f32_e32 v59, 1.0, v59
	v_fma_f32 v190, -v55, v55, 1.0
	v_mul_f32_e32 v58, v58, v189
	v_fmamk_f32 v60, v60, 0xbfb8aa3b, v237
	v_rcp_f32_e32 v56, v56
	v_add_f32_e32 v57, 1.0, v57
	v_rcp_f32_e32 v59, v59
	v_mul_f32_e32 v58, v58, v185
	v_sqrt_f32_e32 v185, v190
	v_exp_f32_e32 v60, v60
	v_rcp_f32_e32 v57, v57
	v_mul_f32_e32 v56, v218, v56
	v_fmamk_f32 v187, v61, 0xbfb8aa3b, v237
	v_mul_f32_e32 v185, v59, v185
	v_add_f32_e32 v59, 1.0, v60
	v_exp_f32_e32 v56, v56
	v_exp_f32_e32 v61, v187
	v_mul_f32_e32 v57, v218, v57
	v_rcp_f32_e32 v60, v59
	v_exp_f32_e32 v59, v57
	v_fma_f32 v186, -v56, v56, 1.0
	v_add_f32_e32 v57, 1.0, v61
	v_sqrt_f32_e32 v186, v186
	v_rcp_f32_e32 v61, v57
	v_fma_f32 v57, -v59, v59, 1.0
	v_sqrt_f32_e32 v187, v57
	v_mul_f32_e32 v60, v60, v186
	v_mul_f32_e32 v60, v60, v177
	v_mul_f32_e32 v177, v59, v56
	v_mul_f32_e32 v61, v61, v187
	v_mul_f32_e32 v61, v61, v184
	v_mul_f32_e32 v177, v55, v177
	v_mul_f32_e32 v186, v54, v177
	v_fma_f32 v177, 0, v59, v61
	v_mul_f32_e32 v57, v185, v183
	v_fma_f32 v177, v56, v177, v60
	v_fma_f32 v177, v55, v177, v57
	v_fma_f32 v189, v54, v177, v58
	v_mov_b32_e32 v188, v186
	v_mov_b32_e32 v177, v189
	s_nop 0
	v_permlane16_swap_b32_e32 v186, v188
	v_permlane16_swap_b32_e32 v189, v177
	v_mov_b32_e32 v183, v188
	v_mov_b32_e32 v185, v177
	v_mov_b32_e32 v187, v186
	v_permlane32_swap_b32_e32 v188, v183
	v_mov_b32_e32 v184, v189
	v_permlane32_swap_b32_e32 v177, v185
	v_permlane32_swap_b32_e32 v186, v187
	v_permlane32_swap_b32_e32 v189, v184
	v_fmac_f32_e32 v185, 0, v183
	v_fmac_f32_e32 v184, v185, v187
	v_mul_f32_e32 v187, v187, v183
	v_fmac_f32_e32 v177, v184, v188
	v_mul_f32_e32 v188, v187, v188
	s_and_saveexec_b64 s[28:29], s[10:11]
	v_mul_f32_e32 v191, v177, v186
	v_mul_f32_e32 v190, v188, v186
	v_add_f32_e32 v191, v191, v189
	ds_write_b64 v150, v[190:191] offset:53248
	s_or_b64 exec, exec, s[28:29]
	v_lshlrev_b32_e32 v197, 16, v219
	v_lshlrev_b32_e32 v195, 16, v220
	v_lshlrev_b32_e32 v194, 16, v221
	v_fmamk_f32 v46, v46, 0xbfb8aa3b, v238
	v_exp_f32_e32 v46, v46
	v_fmamk_f32 v47, v47, 0xbfb8aa3b, v238
	v_fmamk_f32 v50, v50, 0xbfb8aa3b, v239
	v_exp_f32_e32 v47, v47
	v_add_f32_e32 v46, 1.0, v46
	v_rcp_f32_e32 v46, v46
	v_exp_f32_e32 v50, v50
	v_add_f32_e32 v47, 1.0, v47
; template <bool PASS_C>
; DEVI void lru_item(const P& p, int item, int next_item, uint4& u0, uint4& u1, uint4& u2, float& cpre, char* smem) {
;     ...
;         for (int d = 0; d < 2; ++d) {
;             const float ba = prm[(5 + d) * 64 + ch], bx = prm[(7 + d) * 64 + ch], nsp8 = prm[(9 + d) * 64 + ch];
; #pragma unroll
;             for (int j = 0; j < 4; ++j) {
;                 const float r = __builtin_amdgcn_rcpf(1.0f + __builtin_amdgcn_exp2f(__builtin_fmaf(acc[(2 * d) * 4 + nn][j], -LOG2E, ba)));
;                 const float ig = __builtin_amdgcn_rcpf(1.0f + __builtin_amdgcn_exp2f(__builtin_fmaf(acc[(2 * d + 1) * 4 + nn][j], -LOG2E, bx)));
;                 const float a_ = __builtin_amdgcn_exp2f(nsp8 * r);
;                 av[nn][d][j] = a_;
;                 bv[nn][d][j] = __builtin_amdgcn_sqrtf(__builtin_fmaf(-a_, a_, 1.0f)) * ig * uc[j];
;             }
;             float A = 1.f, Bq = 0.f;
;             if (d == 0) {
; #pragma unroll
;                 for (int j = 0; j < 4; ++j) { Bq = av[nn][d][j] * Bq + bv[nn][d][j]; A *= av[nn][d][j]; }
;             } else {
; #pragma unroll
;                 for (int j = 3; j >= 0; --j) { Bq = av[nn][d][j] * Bq + bv[nn][d][j]; A *= av[nn][d][j]; }
;             }
;             float Ag[4], Bg[4];
;             rowgather4(A, Ag); rowgather4(Bq, Bg);
;             float AW = 1.f, BW = 0.f, AP = 1.f, BP = 0.f;
;             if (d == 0) {
; #pragma unroll
;                 for (int g = 0; g < 4; ++g) {
;                     if (g == fq) { AP = AW; BP = BW; }
;                     BW = Ag[g] * BW + Bg[g]; AW *= Ag[g];
;                 }
;             } else {
; #pragma unroll
;                 for (int g = 3; g >= 0; --g) {
;                     if (g == fq) { AP = AW; BP = BW; }
;                     BW = Ag[g] * BW + Bg[g]; AW *= Ag[g];
;                 }
;             }
;             apre[nn][d] = AP; bpre[nn][d] = BP;
;             if (fq == 0) { wagg[((w * 2 + d) * 64 + ch) * 2 + 0] = AW; wagg[((w * 2 + d) * 64 + ch) * 2 + 1] = BW; }
;         }
	v_rcp_f32_e32 v47, v47
	v_mul_f32_e32 v46, v223, v46
	v_add_f32_e32 v186, 1.0, v50
	v_exp_f32_e32 v50, v46
	v_rcp_f32_e32 v46, v186
	v_fmamk_f32 v51, v51, 0xbfb8aa3b, v239
	v_mul_f32_e32 v47, v223, v47
	v_fma_f32 v186, -v50, v50, 1.0
	v_sqrt_f32_e32 v186, v186
	v_exp_f32_e32 v51, v51
	v_exp_f32_e32 v47, v47
	v_fmamk_f32 v48, v48, 0xbfb8aa3b, v238
	v_exp_f32_e32 v48, v48
	v_mul_f32_e32 v46, v46, v186
	v_add_f32_e32 v51, 1.0, v51
	v_fma_f32 v186, -v47, v47, 1.0
	v_rcp_f32_e32 v51, v51
	v_sqrt_f32_e32 v186, v186
	v_add_f32_e32 v48, 1.0, v48
	v_rcp_f32_e32 v48, v48
	v_fmamk_f32 v49, v49, 0xbfb8aa3b, v238
	v_mul_f32_e32 v51, v51, v186
	v_exp_f32_e32 v186, v49
	v_mul_f32_e32 v48, v223, v48
	v_exp_f32_e32 v49, v48
	v_fmamk_f32 v52, v52, 0xbfb8aa3b, v239
	v_add_f32_e32 v48, 1.0, v186
	v_rcp_f32_e32 v48, v48
	v_fmamk_f32 v191, v53, 0xbfb8aa3b, v239
	v_exp_f32_e32 v189, v191
	v_exp_f32_e32 v52, v52
	v_mul_f32_e32 v48, v223, v48
	v_exp_f32_e32 v53, v48
	v_add_f32_e32 v48, 1.0, v189
	v_add_f32_e32 v52, 1.0, v52
	v_fma_f32 v186, -v49, v49, 1.0
	v_rcp_f32_e32 v189, v48
	v_fma_f32 v48, -v53, v53, 1.0
	v_rcp_f32_e32 v52, v52
	v_sqrt_f32_e32 v186, v186
	v_sqrt_f32_e32 v190, v48
	v_mul_f32_e32 v46, v46, v197
	v_mul_f32_e32 v48, v51, v195
	v_mul_f32_e32 v51, v52, v186
	v_mul_f32_e32 v52, v189, v190
	v_fma_f32 v189, 0, v50, v46
	v_lshlrev_b32_e32 v196, 16, v222
	v_mul_f32_e32 v51, v51, v194
	v_mul_f32_e32 v186, v50, v47
	v_fma_f32 v189, v47, v189, v48
	v_mul_f32_e32 v52, v52, v196
	v_mul_f32_e32 v186, v49, v186
	v_fma_f32 v189, v49, v189, v51
	v_mul_f32_e32 v186, v53, v186
	v_fma_f32 v189, v53, v189, v52
	v_mov_b32_e32 v192, v186
	v_mov_b32_e32 v190, v189
	s_nop 0
	v_permlane16_swap_b32_e32 v186, v192
	v_permlane16_swap_b32_e32 v189, v190
	v_mov_b32_e32 v193, v186
	v_mov_b32_e32 v191, v189
	s_nop 0
	v_permlane32_swap_b32_e32 v186, v193
	v_mov_b32_e32 v199, v192
	v_permlane32_swap_b32_e32 v189, v191
	v_mov_b32_e32 v200, v190
	v_permlane32_swap_b32_e32 v192, v199
	s_nop 0
	v_permlane32_swap_b32_e32 v190, v200
	v_fmac_f32_e32 v189, 0, v186
	v_fmac_f32_e32 v190, v189, v192
	v_mul_f32_e32 v192, v186, v192
	v_fmac_f32_e32 v191, v190, v193
	v_mul_f32_e32 v193, v192, v193
	s_and_saveexec_b64 s[28:29], s[10:11]
	v_mul_f32_e32 v201, v191, v199
	v_mul_f32_e32 v202, v193, v199
	v_add_f32_e32 v203, v201, v200
	ds_write_b64 v151, v[202:203] offset:52736
	s_or_b64 exec, exec, s[28:29]
	v_fmamk_f32 v38, v38, 0xbfb8aa3b, v240
	v_exp_f32_e32 v38, v38
	v_fmamk_f32 v39, v39, 0xbfb8aa3b, v240
	v_exp_f32_e32 v39, v39
	v_fmamk_f32 v42, v42, 0xbfb8aa3b, v241
	v_add_f32_e32 v38, 1.0, v38
	v_rcp_f32_e32 v38, v38
	v_add_f32_e32 v39, 1.0, v39
	v_exp_f32_e32 v42, v42
	v_rcp_f32_e32 v39, v39
	v_mul_f32_e32 v38, v224, v38
	v_exp_f32_e32 v38, v38
	v_fmamk_f32 v40, v40, 0xbfb8aa3b, v240
	v_fmamk_f32 v43, v43, 0xbfb8aa3b, v241
	v_add_f32_e32 v42, 1.0, v42
	v_mul_f32_e32 v39, v224, v39
	v_fma_f32 v201, -v38, v38, 1.0
	v_exp_f32_e32 v40, v40
	v_fmamk_f32 v41, v41, 0xbfb8aa3b, v240
	v_exp_f32_e32 v43, v43
	v_rcp_f32_e32 v42, v42
	v_exp_f32_e32 v39, v39
	v_sqrt_f32_e32 v201, v201
	v_exp_f32_e32 v41, v41
	v_add_f32_e32 v40, 1.0, v40
	v_add_f32_e32 v43, 1.0, v43
	v_fma_f32 v202, -v39, v39, 1.0
	v_mul_f32_e32 v42, v42, v201
	v_fmamk_f32 v44, v44, 0xbfb8aa3b, v241
	v_rcp_f32_e32 v40, v40
	v_add_f32_e32 v41, 1.0, v41
	v_rcp_f32_e32 v43, v43
	v_mul_f32_e32 v42, v42, v197
	v_sqrt_f32_e32 v197, v202
	v_exp_f32_e32 v44, v44
	v_rcp_f32_e32 v41, v41
	v_mul_f32_e32 v40, v224, v40
	v_fmamk_f32 v199, v45, 0xbfb8aa3b, v241
	v_mul_f32_e32 v197, v43, v197
	v_add_f32_e32 v43, 1.0, v44
	v_exp_f32_e32 v40, v40
	v_exp_f32_e32 v45, v199
	v_mul_f32_e32 v41, v224, v41
	v_rcp_f32_e32 v44, v43
	v_exp_f32_e32 v43, v41
	v_fma_f32 v198, -v40, v40, 1.0
	v_add_f32_e32 v41, 1.0, v45
	v_sqrt_f32_e32 v198, v198
	v_rcp_f32_e32 v45, v41
	v_fma_f32 v41, -v43, v43, 1.0
	v_sqrt_f32_e32 v199, v41
	v_mul_f32_e32 v44, v44, v198
	v_mul_f32_e32 v44, v44, v194
	v_mul_f32_e32 v194, v43, v40
	v_mul_f32_e32 v45, v45, v199
	v_mul_f32_e32 v45, v45, v196
	v_mul_f32_e32 v194, v39, v194
	v_mul_f32_e32 v198, v38, v194
	v_fma_f32 v194, 0, v43, v45
	v_mul_f32_e32 v41, v197, v195
	v_fma_f32 v194, v40, v194, v44
	v_fma_f32 v194, v39, v194, v41
	v_fma_f32 v200, v38, v194, v42
	v_mov_b32_e32 v201, v198
	v_mov_b32_e32 v194, v200
	s_nop 0
	v_permlane16_swap_b32_e32 v198, v201
	v_permlane16_swap_b32_e32 v200, v194
	v_mov_b32_e32 v195, v201
	v_mov_b32_e32 v197, v194
	v_mov_b32_e32 v199, v198
	v_permlane32_swap_b32_e32 v201, v195
	v_mov_b32_e32 v196, v200
	v_permlane32_swap_b32_e32 v194, v197
	v_permlane32_swap_b32_e32 v198, v199
	v_permlane32_swap_b32_e32 v200, v196
	v_fmac_f32_e32 v197, 0, v195
	v_fmac_f32_e32 v196, v197, v199
	v_mul_f32_e32 v199, v199, v195
	v_fmac_f32_e32 v194, v196, v201
	v_mul_f32_e32 v201, v199, v201
	s_and_saveexec_b64 s[28:29], s[10:11]
	v_mul_f32_e32 v203, v194, v198
	v_mul_f32_e32 v202, v201, v198
	v_add_f32_e32 v203, v203, v200
	ds_write_b64 v151, v[202:203] offset:53248
	s_or_b64 exec, exec, s[28:29]
	v_lshlrev_b32_e32 v209, 16, v225
	v_lshlrev_b32_e32 v207, 16, v226
	v_lshlrev_b32_e32 v206, 16, v227
	v_fmamk_f32 v30, v30, 0xbfb8aa3b, v242
	v_exp_f32_e32 v30, v30
	v_fmamk_f32 v31, v31, 0xbfb8aa3b, v242
	v_fmamk_f32 v34, v34, 0xbfb8aa3b, v243
	v_exp_f32_e32 v31, v31
	v_add_f32_e32 v30, 1.0, v30
	v_rcp_f32_e32 v30, v30
	v_exp_f32_e32 v34, v34
	v_add_f32_e32 v31, 1.0, v31
	v_rcp_f32_e32 v31, v31
	v_mul_f32_e32 v30, v229, v30
	v_add_f32_e32 v198, 1.0, v34
	v_exp_f32_e32 v34, v30
	v_rcp_f32_e32 v30, v198
	v_fmamk_f32 v35, v35, 0xbfb8aa3b, v243
	v_mul_f32_e32 v31, v229, v31
	v_fma_f32 v198, -v34, v34, 1.0
	v_sqrt_f32_e32 v198, v198
; template <bool PASS_C>
; DEVI void lru_item(const P& p, int item, int next_item, uint4& u0, uint4& u1, uint4& u2, float& cpre, char* smem) {
;     ...
;         for (int d = 0; d < 2; ++d) {
;             const float ba = prm[(5 + d) * 64 + ch], bx = prm[(7 + d) * 64 + ch], nsp8 = prm[(9 + d) * 64 + ch];
; #pragma unroll
;             for (int j = 0; j < 4; ++j) {
;                 const float r = __builtin_amdgcn_rcpf(1.0f + __builtin_amdgcn_exp2f(__builtin_fmaf(acc[(2 * d) * 4 + nn][j], -LOG2E, ba)));
;                 const float ig = __builtin_amdgcn_rcpf(1.0f + __builtin_amdgcn_exp2f(__builtin_fmaf(acc[(2 * d + 1) * 4 + nn][j], -LOG2E, bx)));
;                 const float a_ = __builtin_amdgcn_exp2f(nsp8 * r);
;                 av[nn][d][j] = a_;
;                 bv[nn][d][j] = __builtin_amdgcn_sqrtf(__builtin_fmaf(-a_, a_, 1.0f)) * ig * uc[j];
;             }
;             float A = 1.f, Bq = 0.f;
;             if (d == 0) {
; #pragma unroll
;                 for (int j = 0; j < 4; ++j) { Bq = av[nn][d][j] * Bq + bv[nn][d][j]; A *= av[nn][d][j]; }
;             } else {
; #pragma unroll
;                 for (int j = 3; j >= 0; --j) { Bq = av[nn][d][j] * Bq + bv[nn][d][j]; A *= av[nn][d][j]; }
;             }
;             float Ag[4], Bg[4];
;             rowgather4(A, Ag); rowgather4(Bq, Bg);
;             float AW = 1.f, BW = 0.f, AP = 1.f, BP = 0.f;
;             if (d == 0) {
; #pragma unroll
;                 for (int g = 0; g < 4; ++g) {
;                     if (g == fq) { AP = AW; BP = BW; }
;                     BW = Ag[g] * BW + Bg[g]; AW *= Ag[g];
;                 }
;             } else {
; #pragma unroll
;                 for (int g = 3; g >= 0; --g) {
;                     if (g == fq) { AP = AW; BP = BW; }
;                     BW = Ag[g] * BW + Bg[g]; AW *= Ag[g];
;                 }
;             }
;             apre[nn][d] = AP; bpre[nn][d] = BP;
;             if (fq == 0) { wagg[((w * 2 + d) * 64 + ch) * 2 + 0] = AW; wagg[((w * 2 + d) * 64 + ch) * 2 + 1] = BW; }
;         }
;     }
;     __syncthreads();
	v_exp_f32_e32 v35, v35
	v_exp_f32_e32 v31, v31
	v_fmamk_f32 v32, v32, 0xbfb8aa3b, v242
	v_exp_f32_e32 v32, v32
	v_mul_f32_e32 v30, v30, v198
	v_add_f32_e32 v35, 1.0, v35
	v_fma_f32 v198, -v31, v31, 1.0
	v_rcp_f32_e32 v35, v35
	v_sqrt_f32_e32 v198, v198
	v_add_f32_e32 v32, 1.0, v32
	v_rcp_f32_e32 v32, v32
	v_fmamk_f32 v33, v33, 0xbfb8aa3b, v242
	v_mul_f32_e32 v35, v35, v198
	v_exp_f32_e32 v198, v33
	v_mul_f32_e32 v32, v229, v32
	v_exp_f32_e32 v33, v32
	v_fmamk_f32 v36, v36, 0xbfb8aa3b, v243
	v_add_f32_e32 v32, 1.0, v198
	v_rcp_f32_e32 v32, v32
	v_fmamk_f32 v203, v37, 0xbfb8aa3b, v243
	v_exp_f32_e32 v200, v203
	v_exp_f32_e32 v36, v36
	v_mul_f32_e32 v32, v229, v32
	v_exp_f32_e32 v37, v32
	v_add_f32_e32 v32, 1.0, v200
	v_add_f32_e32 v36, 1.0, v36
	v_fma_f32 v198, -v33, v33, 1.0
	v_rcp_f32_e32 v200, v32
	v_fma_f32 v32, -v37, v37, 1.0
	v_rcp_f32_e32 v36, v36
	v_sqrt_f32_e32 v198, v198
	v_sqrt_f32_e32 v202, v32
	v_mul_f32_e32 v30, v30, v209
	v_mul_f32_e32 v32, v35, v207
	v_mul_f32_e32 v35, v36, v198
	v_mul_f32_e32 v36, v200, v202
	v_fma_f32 v200, 0, v34, v30
	v_lshlrev_b32_e32 v208, 16, v228
	v_mul_f32_e32 v35, v35, v206
	v_mul_f32_e32 v198, v34, v31
	v_fma_f32 v200, v31, v200, v32
	v_mul_f32_e32 v36, v36, v208
	v_mul_f32_e32 v198, v33, v198
	v_fma_f32 v200, v33, v200, v35
	v_mul_f32_e32 v198, v37, v198
	v_fma_f32 v200, v37, v200, v36
	v_mov_b32_e32 v204, v198
	v_mov_b32_e32 v202, v200
	s_nop 0
	v_permlane16_swap_b32_e32 v198, v204
	v_permlane16_swap_b32_e32 v200, v202
	v_mov_b32_e32 v205, v198
	v_mov_b32_e32 v203, v200
	s_nop 0
	v_permlane32_swap_b32_e32 v198, v205
	v_mov_b32_e32 v211, v204
	v_permlane32_swap_b32_e32 v200, v203
	v_mov_b32_e32 v212, v202
	v_permlane32_swap_b32_e32 v204, v211
	s_nop 0
	v_permlane32_swap_b32_e32 v202, v212
	v_fmac_f32_e32 v200, 0, v198
	v_fmac_f32_e32 v202, v200, v204
	v_mul_f32_e32 v204, v198, v204
	v_fmac_f32_e32 v203, v202, v205
	v_mul_f32_e32 v205, v204, v205
	s_and_saveexec_b64 s[28:29], s[10:11]
	v_mul_f32_e32 v213, v203, v211
	v_mul_f32_e32 v214, v205, v211
	v_add_f32_e32 v215, v213, v212
	ds_write_b64 v152, v[214:215] offset:52736
	s_or_b64 exec, exec, s[28:29]
	v_fmamk_f32 v22, v22, 0xbfb8aa3b, v244
	v_exp_f32_e32 v22, v22
	v_fmamk_f32 v23, v23, 0xbfb8aa3b, v244
	v_exp_f32_e32 v23, v23
	v_fmamk_f32 v26, v26, 0xbfb8aa3b, v245
	v_add_f32_e32 v22, 1.0, v22
	v_rcp_f32_e32 v22, v22
	v_add_f32_e32 v23, 1.0, v23
	v_exp_f32_e32 v26, v26
	v_rcp_f32_e32 v23, v23
	v_mul_f32_e32 v22, v231, v22
	v_exp_f32_e32 v22, v22
	v_fmamk_f32 v24, v24, 0xbfb8aa3b, v244
	v_fmamk_f32 v27, v27, 0xbfb8aa3b, v245
	v_add_f32_e32 v26, 1.0, v26
	v_mul_f32_e32 v23, v231, v23
	v_fma_f32 v213, -v22, v22, 1.0
	v_exp_f32_e32 v24, v24
	v_fmamk_f32 v25, v25, 0xbfb8aa3b, v244
	v_exp_f32_e32 v27, v27
	v_rcp_f32_e32 v26, v26
	v_exp_f32_e32 v23, v23
	v_sqrt_f32_e32 v213, v213
	v_exp_f32_e32 v25, v25
	v_add_f32_e32 v24, 1.0, v24
	v_add_f32_e32 v27, 1.0, v27
	v_fma_f32 v214, -v23, v23, 1.0
	v_mul_f32_e32 v26, v26, v213
	v_fmamk_f32 v28, v28, 0xbfb8aa3b, v245
	v_rcp_f32_e32 v24, v24
	v_add_f32_e32 v25, 1.0, v25
	v_rcp_f32_e32 v27, v27
	v_mul_f32_e32 v26, v26, v209
	v_sqrt_f32_e32 v209, v214
	v_exp_f32_e32 v28, v28
	v_rcp_f32_e32 v25, v25
	v_mul_f32_e32 v24, v231, v24
	v_fmamk_f32 v211, v29, 0xbfb8aa3b, v245
	v_mul_f32_e32 v209, v27, v209
	v_add_f32_e32 v27, 1.0, v28
	v_exp_f32_e32 v24, v24
	v_exp_f32_e32 v29, v211
	v_mul_f32_e32 v25, v231, v25
	v_rcp_f32_e32 v28, v27
	v_exp_f32_e32 v27, v25
	v_fma_f32 v210, -v24, v24, 1.0
	v_add_f32_e32 v25, 1.0, v29
	v_sqrt_f32_e32 v210, v210
	v_rcp_f32_e32 v29, v25
	v_fma_f32 v25, -v27, v27, 1.0
	v_sqrt_f32_e32 v211, v25
	v_mul_f32_e32 v28, v28, v210
	v_mul_f32_e32 v28, v28, v206
	v_mul_f32_e32 v206, v27, v24
	v_mul_f32_e32 v29, v29, v211
	v_mul_f32_e32 v29, v29, v208
	v_mul_f32_e32 v206, v23, v206
	v_mul_f32_e32 v212, v22, v206
	v_fma_f32 v206, 0, v27, v29
	v_mul_f32_e32 v25, v209, v207
	v_fma_f32 v206, v24, v206, v28
	v_fma_f32 v206, v23, v206, v25
	v_fma_f32 v213, v22, v206, v26
	v_mov_b32_e32 v211, v212
	v_mov_b32_e32 v207, v213
	s_nop 0
	v_permlane16_swap_b32_e32 v212, v211
	v_permlane16_swap_b32_e32 v213, v207
	v_mov_b32_e32 v206, v211
	v_mov_b32_e32 v209, v207
	v_mov_b32_e32 v210, v212
	v_permlane32_swap_b32_e32 v211, v206
	v_mov_b32_e32 v208, v213
	v_permlane32_swap_b32_e32 v207, v209
	v_permlane32_swap_b32_e32 v212, v210
	v_permlane32_swap_b32_e32 v213, v208
	v_fmac_f32_e32 v209, 0, v206
	v_fmac_f32_e32 v208, v209, v210
	v_mul_f32_e32 v210, v210, v206
	v_fmac_f32_e32 v207, v208, v211
	v_mul_f32_e32 v211, v210, v211
	s_and_saveexec_b64 s[28:29], s[10:11]
	v_mul_f32_e32 v214, v207, v212
	v_mul_f32_e32 v212, v211, v212
	v_add_f32_e32 v213, v214, v213
	ds_write_b64 v152, v[212:213] offset:53248
	s_or_b64 exec, exec, s[28:29]
	s_waitcnt lgkmcnt(0)
	s_barrier
; template <bool PASS_C>
; DEVI void lru_item(const P& p, int item, int next_item, uint4& u0, uint4& u1, uint4& u2, float& cpre, char* smem) {
;     ...
; #pragma unroll
;         for (int nn = 0; nn < 4; ++nn) {
;             const int ch = 16 * nn + fr;
;             float y[4];
;             {
;                 float hw = carry[ch];
; #pragma unroll
;                 for (int ww = 0; ww < 4; ++ww)
;                     if (ww < w) hw = wagg[((ww * 2 + 0) * 64 + ch) * 2] * hw + wagg[((ww * 2 + 0) * 64 + ch) * 2 + 1];
;                 float hh = apre[nn][0] * hw + bpre[nn][0];
; #pragma unroll
;                 for (int j = 0; j < 4; ++j) { hh = av[nn][0][j] * hh + bv[nn][0][j]; y[j] = hh; }
;             }
;             {
;                 float hw = carry[64 + ch];
; #pragma unroll
;     ...
;                     if (ww > w) hw = wagg[((ww * 2 + 1) * 64 + ch) * 2] * hw + wagg[((ww * 2 + 1) * 64 + ch) * 2 + 1];
;                 float hh = apre[nn][1] * hw + bpre[nn][1];
; #pragma unroll
;                 for (int j = 3; j >= 0; --j) { hh = av[nn][1][j] * hh + bv[nn][1][j]; y[j] += hh; }
;             }
; #pragma unroll
;             for (int j = 0; j < 4; ++j) ytile[(16 * w + 4 * fq + j) * 66 + ch] = y[j];
;         }
	ds_read_b32 v244, v122 offset:56832
	ds_read_b32 v245, v122 offset:57088
	ds_read_b64 v[232:233], v123 offset:52736
	ds_read_b64 v[234:235], v123 offset:53760
	ds_read_b64 v[236:237], v123 offset:54784
	ds_read_b64 v[238:239], v123 offset:56320
	ds_read_b64 v[240:241], v123 offset:55296
	ds_read_b64 v[242:243], v123 offset:54272
	ds_read_b32 v246, v122 offset:56896
	ds_read_b32 v247, v122 offset:57152
	ds_read_b64 v[218:219], v154 offset:52736
	ds_read_b64 v[220:221], v154 offset:53760
	ds_read_b64 v[222:223], v154 offset:54784
	ds_read_b64 v[224:225], v154 offset:56320
	ds_read_b64 v[226:227], v154 offset:55296
	ds_read_b64 v[228:229], v154 offset:54272
	s_waitcnt lgkmcnt(8)
	v_fma_f32 v248, v232, v244, v233
	v_cndmask_b32_e64 v212, v244, v248, s[4:5]
	v_fma_f32 v248, v234, v212, v235
	v_cndmask_b32_e64 v212, v212, v248, s[18:19]
	v_fma_f32 v248, v236, v212, v237
	v_cndmask_b32_e64 v212, v212, v248, s[20:21]
	v_fma_f32 v248, v238, v245, v239
	v_cndmask_b32_e64 v213, v245, v248, s[24:25]
	v_fma_f32 v248, v240, v213, v241
	v_cndmask_b32_e64 v213, v213, v248, s[8:9]
	v_fma_f32 v248, v242, v213, v243
	v_cndmask_b32_e64 v213, v213, v248, s[2:3]
	v_cndmask_b32_e64 v103, 1.0, v103, s[12:13]
	v_cndmask_b32_e64 v105, 0, v105, s[12:13]
	v_cndmask_b32_e64 v103, v103, v159, s[14:15]
	v_cndmask_b32_e64 v105, v105, v157, s[14:15]
	v_cndmask_b32_e64 v103, v103, v160, s[16:17]
	v_cndmask_b32_e64 v105, v105, v158, s[16:17]
	v_fmac_f32_e32 v105, v103, v212
	v_fmac_f32_e32 v87, v89, v105
	v_fmac_f32_e32 v93, v91, v87
	v_cndmask_b32_e64 v89, 1.0, v162, s[14:15]
	v_cndmask_b32_e64 v91, 0, v164, s[14:15]
	v_cndmask_b32_e64 v89, v89, v166, s[12:13]
	v_cndmask_b32_e64 v91, v91, v163, s[12:13]
	v_cndmask_b32_e64 v89, v89, v167, s[10:11]
	v_cndmask_b32_e64 v91, v91, v161, s[10:11]
	v_fmac_f32_e32 v91, v89, v213
	v_fmac_f32_e32 v77, v75, v91
	v_fmac_f32_e32 v76, v72, v77
	v_fmac_f32_e32 v73, v71, v76
	v_fmac_f32_e32 v97, v95, v93
	v_fmac_f32_e32 v74, v70, v73
	v_fmac_f32_e32 v99, v101, v97
	v_add_f32_e32 v71, v93, v73
	v_add_f32_e32 v73, v87, v74
	v_add_u32_e32 v70, 0x8c00, v153
	v_add_f32_e32 v75, v99, v77
	v_add_f32_e32 v72, v97, v76
	ds_write2_b32 v70, v73, v71 offset1:66
	ds_write2_b32 v70, v72, v75 offset0:132 offset1:198
	ds_read_b32 v244, v122 offset:56960
	ds_read_b32 v245, v122 offset:57216
	ds_read_b64 v[232:233], v155 offset:52736
	ds_read_b64 v[234:235], v155 offset:53760
	ds_read_b64 v[236:237], v155 offset:54784
	ds_read_b64 v[238:239], v155 offset:56320
	ds_read_b64 v[240:241], v155 offset:55296
	ds_read_b64 v[242:243], v155 offset:54272
	s_waitcnt lgkmcnt(10)
	v_fma_f32 v248, v218, v246, v219
	v_cndmask_b32_e64 v71, v246, v248, s[4:5]
	v_fma_f32 v248, v220, v71, v221
	v_cndmask_b32_e64 v71, v71, v248, s[18:19]
	v_fma_f32 v248, v222, v71, v223
	v_cndmask_b32_e64 v71, v71, v248, s[20:21]
	v_fma_f32 v248, v224, v247, v225
	v_cndmask_b32_e64 v72, v247, v248, s[24:25]
	v_fma_f32 v248, v226, v72, v227
	v_cndmask_b32_e64 v72, v72, v248, s[8:9]
	v_fma_f32 v248, v228, v72, v229
	v_cndmask_b32_e64 v72, v72, v248, s[2:3]
	v_cndmask_b32_e64 v73, 1.0, v165, s[12:13]
	v_cndmask_b32_e64 v74, 0, v168, s[12:13]
	v_cndmask_b32_e64 v73, v73, v171, s[14:15]
	v_cndmask_b32_e64 v74, v74, v169, s[14:15]
	v_cndmask_b32_e64 v73, v73, v173, s[16:17]
	v_cndmask_b32_e64 v74, v74, v170, s[16:17]
	v_fmac_f32_e32 v74, v73, v71
	v_fmac_f32_e32 v62, v66, v74
	v_fmac_f32_e32 v64, v63, v62
	v_fmac_f32_e32 v67, v65, v64
	v_cndmask_b32_e64 v63, 1.0, v183, s[14:15]
	v_cndmask_b32_e64 v65, 0, v185, s[14:15]
	v_cndmask_b32_e64 v63, v63, v187, s[12:13]
	v_cndmask_b32_e64 v65, v65, v184, s[12:13]
	v_cndmask_b32_e64 v63, v63, v188, s[10:11]
	v_cndmask_b32_e64 v65, v65, v177, s[10:11]
	v_fmac_f32_e32 v65, v63, v72
	v_fmac_f32_e32 v61, v59, v65
	v_fmac_f32_e32 v60, v56, v61
	v_fmac_f32_e32 v57, v55, v60
	v_fmac_f32_e32 v58, v54, v57
	v_fmac_f32_e32 v68, v69, v67
	v_add_f32_e32 v55, v64, v57
	v_add_f32_e32 v54, v62, v58
	v_add_f32_e32 v59, v68, v61
	v_add_f32_e32 v56, v67, v60
	ds_write2_b32 v70, v54, v55 offset0:16 offset1:82
	ds_write2_b32 v70, v56, v59 offset0:148 offset1:214
	ds_read_b32 v246, v122 offset:57024
	ds_read_b32 v247, v122 offset:57280
	ds_read_b64 v[218:219], v156 offset:52736
	ds_read_b64 v[220:221], v156 offset:53760
	ds_read_b64 v[222:223], v156 offset:54784
	ds_read_b64 v[224:225], v156 offset:56320
	ds_read_b64 v[226:227], v156 offset:55296
	ds_read_b64 v[228:229], v156 offset:54272
	s_waitcnt lgkmcnt(10)
	v_fma_f32 v248, v232, v244, v233
	v_cndmask_b32_e64 v54, v244, v248, s[4:5]
	v_fma_f32 v248, v234, v54, v235
	v_cndmask_b32_e64 v54, v54, v248, s[18:19]
	v_fma_f32 v248, v236, v54, v237
	v_cndmask_b32_e64 v54, v54, v248, s[20:21]
	v_fma_f32 v248, v238, v245, v239
	v_cndmask_b32_e64 v55, v245, v248, s[24:25]
	v_fma_f32 v248, v240, v55, v241
	v_cndmask_b32_e64 v55, v55, v248, s[8:9]
	v_fma_f32 v248, v242, v55, v243
	v_cndmask_b32_e64 v55, v55, v248, s[2:3]
	v_cndmask_b32_e64 v56, 1.0, v186, s[12:13]
	v_cndmask_b32_e64 v57, 0, v189, s[12:13]
	v_cndmask_b32_e64 v56, v56, v192, s[14:15]
	v_cndmask_b32_e64 v57, v57, v190, s[14:15]
	v_cndmask_b32_e64 v56, v56, v193, s[16:17]
	v_cndmask_b32_e64 v57, v57, v191, s[16:17]
	v_fmac_f32_e32 v57, v56, v54
	v_fmac_f32_e32 v46, v50, v57
	v_fmac_f32_e32 v48, v47, v46
	v_fmac_f32_e32 v51, v49, v48
	v_cndmask_b32_e64 v47, 1.0, v195, s[14:15]
	v_cndmask_b32_e64 v49, 0, v197, s[14:15]
	v_cndmask_b32_e64 v47, v47, v199, s[12:13]
	v_cndmask_b32_e64 v49, v49, v196, s[12:13]
	v_cndmask_b32_e64 v47, v47, v201, s[10:11]
	v_cndmask_b32_e64 v49, v49, v194, s[10:11]
	v_fmac_f32_e32 v49, v47, v55
	v_fmac_f32_e32 v45, v43, v49
	v_fmac_f32_e32 v44, v40, v45
	v_fmac_f32_e32 v41, v39, v44
	v_fmac_f32_e32 v42, v38, v41
	v_fmac_f32_e32 v52, v53, v51
	v_add_f32_e32 v39, v48, v41
	v_add_f32_e32 v38, v46, v42
	v_add_f32_e32 v43, v52, v45
	v_add_f32_e32 v40, v51, v44
	ds_write2_b32 v70, v38, v39 offset0:32 offset1:98
	ds_write2_b32 v70, v40, v43 offset0:164 offset1:230
	s_waitcnt lgkmcnt(2)
	v_fma_f32 v248, v218, v246, v219
	v_cndmask_b32_e64 v38, v246, v248, s[4:5]
	v_fma_f32 v248, v220, v38, v221
	v_cndmask_b32_e64 v38, v38, v248, s[18:19]
	v_fma_f32 v248, v222, v38, v223
	v_cndmask_b32_e64 v38, v38, v248, s[20:21]
	v_fma_f32 v248, v224, v247, v225
	v_cndmask_b32_e64 v39, v247, v248, s[24:25]
	v_fma_f32 v248, v226, v39, v227
	v_cndmask_b32_e64 v39, v39, v248, s[8:9]
	v_fma_f32 v248, v228, v39, v229
	v_cndmask_b32_e64 v39, v39, v248, s[2:3]
	s_branch .LBB0_720
